# GEMM K-loops: no per-segment s_setprio; one static s_setprio 1 for waves 4-7 per GEMM unit (reset to 0 at phase end)
# baseline (speedup 1.0000x reference)
; #define PG8_STAGE(bufoff, gbase, voff) do { _Pragma("unroll") for (int _i = 0; _i < 2; ++_i) \
;         __builtin_amdgcn_global_load_lds((const unsigned*)((const char*)(gbase) + (voff)[_i]), (PG8_LAS unsigned*)(lds + (bufoff) + ldsw + _i * 8192), 16, 0, 0); } while (0)
; #define PG8_LDA(dst, b, h) do { _Pragma("unroll") for (int m = 0; m < 4; ++m) _Pragma("unroll") for (int k = 0; k < 2; ++k) dst[m][k] = *(const PG8_LAS bf16x8*)(lds + PG8_SA(b, h) + aoff + m * 2048 + k * 1024); } while (0)
; #define PG8_LDB(dst, b, h) do { _Pragma("unroll") for (int n = 0; n < 2; ++n) _Pragma("unroll") for (int k = 0; k < 2; ++k) dst[n][k] = *(const PG8_LAS bf16x8*)(lds + PG8_SB(b, h) + boff + n * 2048 + k * 1024); } while (0)
; #define PG8_SCHED __builtin_amdgcn_sched_barrier(0)
; template <class Epi, class Sched, bool ALIGN_EPI = false, bool SP2 = false>
; __device__ __forceinline__ void gemm_phase(PG8_LAS unsigned char* lds, const Gemm g, const Sched& S, const Epi& E) {
;     ...
;         const bool has_next = S.next(ui + 1, nxt);
;         const char* nA = has_next ? (const char*)g.A + (size_t)nxt.pm * tstep : cA; const char* nB = has_next ? (const char*)g.Bt + (size_t)nxt.pn * tstep : cB;
;         for (int t = 0; t < nt; t += 2) {
;             const bool last = (t == nt - 2);
;             const char* a1 = cA + (size_t)(t + 1) * kstep;
;             const char* a2 = last ? nA : cA + (size_t)(t + 2) * kstep; const char* b2 = last ? nB : cB + (size_t)(t + 2) * kstep;
;             const char* a3 = a2 + kstep; const char* b3 = b2 + kstep;
;             if (last && has_next) S.a_ready(nxt);
;             if constexpr (SP2) {
;             PG8_LDB(B0, 0, 0); PG8_LDB(B1, 0, 1); PG8_SCHED; PG8_LDA(At, 0, 0); PG8_STAGE(PG8_SA(1, 1), a1 + hstep, voffA);
;     ...
;         for (int a = 0; a < 2; ++a)
; #pragma unroll
;             for (int b = 0; b < 2; ++b)
; #pragma unroll
;                 for (int m = 0; m < 4; ++m)
; #pragma unroll
;                     for (int n = 0; n < 2; ++n) acc[a][b][m][n] = (f32x4){0.f, 0.f, 0.f, 0.f};
.LBB0_416:
	s_ashr_i32 s43, s42, 31
	s_lshl_b64 s[0:1], s[42:43], 20
	v_readlane_b32 s4, v254, 59
	v_readlane_b32 s5, v254, 60
	s_add_u32 s56, s4, s0
	s_addc_u32 s57, s5, s1
	s_and_b64 s[0:1], s[38:39], exec
	s_cselect_b32 s7, s57, s65
	s_cselect_b32 s8, s56, s64
	s_ashr_i32 s37, s36, 31
	s_lshl_b64 s[0:1], s[36:37], 20
	s_add_u32 s62, s59, s0
	s_addc_u32 s63, s66, s1
	s_and_b64 s[0:1], s[38:39], exec
	s_cselect_b32 s9, s63, s41
	s_cselect_b32 s14, s62, s40
	s_add_u32 s15, s40, 0x100
	s_addc_u32 s17, s41, 0
	s_add_u32 s40, s64, 0x80080
	v_mov_b32_e32 v0, 0
	s_addc_u32 s41, s65, 0
	s_mov_b32 s19, -2
	v_mov_b32_e32 v1, v0
	v_mov_b32_e32 v2, v0
	v_mov_b32_e32 v3, v0
	v_mov_b32_e32 v4, v0
	v_mov_b32_e32 v5, v0
	v_mov_b32_e32 v6, v0
	v_mov_b32_e32 v7, v0
	v_mov_b32_e32 v16, v0
	v_mov_b32_e32 v17, v0
	v_mov_b32_e32 v18, v0
	v_mov_b32_e32 v19, v0
	v_mov_b32_e32 v20, v0
	v_mov_b32_e32 v21, v0
	v_mov_b32_e32 v22, v0
	v_mov_b32_e32 v23, v0
	v_mov_b32_e32 v32, v0
	v_mov_b32_e32 v33, v0
	v_mov_b32_e32 v34, v0
	v_mov_b32_e32 v35, v0
	v_mov_b32_e32 v36, v0
	v_mov_b32_e32 v37, v0
	v_mov_b32_e32 v38, v0
	v_mov_b32_e32 v39, v0
	v_mov_b32_e32 v48, v0
	v_mov_b32_e32 v49, v0
	v_mov_b32_e32 v50, v0
	v_mov_b32_e32 v51, v0
	v_mov_b32_e32 v52, v0
	v_mov_b32_e32 v53, v0
	v_mov_b32_e32 v54, v0
	v_mov_b32_e32 v55, v0
	v_mov_b32_e32 v8, v0
	v_mov_b32_e32 v9, v0
	v_mov_b32_e32 v10, v0
	v_mov_b32_e32 v11, v0
	v_mov_b32_e32 v12, v0
	v_mov_b32_e32 v13, v0
	v_mov_b32_e32 v14, v0
	v_mov_b32_e32 v15, v0
	v_mov_b32_e32 v24, v0
	v_mov_b32_e32 v25, v0
	v_mov_b32_e32 v26, v0
	v_mov_b32_e32 v27, v0
	v_mov_b32_e32 v28, v0
	v_mov_b32_e32 v29, v0
	v_mov_b32_e32 v30, v0
	v_mov_b32_e32 v31, v0
	v_mov_b32_e32 v40, v0
	v_mov_b32_e32 v41, v0
	v_mov_b32_e32 v42, v0
	v_mov_b32_e32 v43, v0
	v_mov_b32_e32 v44, v0
	v_mov_b32_e32 v45, v0
	v_mov_b32_e32 v46, v0
	v_mov_b32_e32 v47, v0
	v_mov_b32_e32 v56, v0
	v_mov_b32_e32 v57, v0
	v_mov_b32_e32 v58, v0
	v_mov_b32_e32 v59, v0
	v_mov_b32_e32 v60, v0
	v_mov_b32_e32 v61, v0
	v_mov_b32_e32 v62, v0
	v_mov_b32_e32 v63, v0
	v_mov_b32_e32 v64, v0
	v_mov_b32_e32 v65, v0
	v_mov_b32_e32 v66, v0
	v_mov_b32_e32 v67, v0
	v_mov_b32_e32 v68, v0
	v_mov_b32_e32 v69, v0
	v_mov_b32_e32 v70, v0
	v_mov_b32_e32 v71, v0
	v_mov_b32_e32 v80, v0
	v_mov_b32_e32 v81, v0
	v_mov_b32_e32 v82, v0
	v_mov_b32_e32 v83, v0
	v_mov_b32_e32 v84, v0
	v_mov_b32_e32 v85, v0
	v_mov_b32_e32 v86, v0
	v_mov_b32_e32 v87, v0
	v_mov_b32_e32 v98, v0
	v_mov_b32_e32 v99, v0
	v_mov_b32_e32 v100, v0
	v_mov_b32_e32 v101, v0
	v_mov_b32_e32 v102, v0
	v_mov_b32_e32 v103, v0
	v_mov_b32_e32 v104, v0
	v_mov_b32_e32 v105, v0
	v_mov_b32_e32 v114, v0
	v_mov_b32_e32 v115, v0
	v_mov_b32_e32 v116, v0
	v_mov_b32_e32 v117, v0
	v_mov_b32_e32 v118, v0
	v_mov_b32_e32 v119, v0
	v_mov_b32_e32 v120, v0
	v_mov_b32_e32 v121, v0
	v_mov_b32_e32 v72, v0
	v_mov_b32_e32 v73, v0
	v_mov_b32_e32 v74, v0
	v_mov_b32_e32 v75, v0
	v_mov_b32_e32 v76, v0
	v_mov_b32_e32 v77, v0
	v_mov_b32_e32 v78, v0
	v_mov_b32_e32 v79, v0
	v_mov_b32_e32 v88, v0
	v_mov_b32_e32 v89, v0
	v_mov_b32_e32 v90, v0
	v_mov_b32_e32 v91, v0
	v_mov_b32_e32 v92, v0
	v_mov_b32_e32 v93, v0
	v_mov_b32_e32 v94, v0
	v_mov_b32_e32 v95, v0
	v_mov_b32_e32 v106, v0
	v_mov_b32_e32 v107, v0
	v_mov_b32_e32 v108, v0
	v_mov_b32_e32 v109, v0
	v_mov_b32_e32 v110, v0
	v_mov_b32_e32 v111, v0
	v_mov_b32_e32 v112, v0
	v_mov_b32_e32 v113, v0
	v_mov_b32_e32 v122, v0
	v_mov_b32_e32 v123, v0
	v_mov_b32_e32 v124, v0
	v_mov_b32_e32 v125, v0
	v_mov_b32_e32 v126, v0
	v_mov_b32_e32 v127, v0
	v_mov_b32_e32 v128, v0
	v_mov_b32_e32 v129, v0
	s_cmp_lg_u64 s[34:35], 0
	s_cbranch_scc1 .Lgp_a
	s_setprio 1
.Lgp_a:
.LBB0_417:
	s_add_u32 s0, s40, 0xfff80080
	s_addc_u32 s1, s41, -1
	s_add_i32 s30, 0, 0x10000
	s_cmp_eq_u32 s19, 28
	s_cselect_b32 s5, s7, s1
	s_cselect_b32 s4, s8, s0
	s_cselect_b32 s1, s9, s17
	s_cselect_b32 s0, s14, s15
	s_add_i32 s33, 0, 0x14000
	v_add_u32_e32 v142, s30, v203
	v_add_u32_e32 v158, s33, v203
	ds_read_b128 v[130:133], v142
	ds_read_b128 v[134:137], v142 offset:1024
	ds_read_b128 v[138:141], v142 offset:2048
	ds_read_b128 v[142:145], v142 offset:3072
	ds_read_b128 v[146:149], v158
	ds_read_b128 v[150:153], v158 offset:1024
	ds_read_b128 v[154:157], v158 offset:2048
	ds_read_b128 v[158:161], v158 offset:3072
	v_lshl_add_u64 v[190:191], s[40:41], 0, v[188:189]
	s_add_i32 m0, s67, 0xc000
	ds_read_b128 v[162:165], v209
	ds_read_b128 v[166:169], v209 offset:1024
	ds_read_b128 v[170:173], v209 offset:2048
	ds_read_b128 v[174:177], v209 offset:3072
	ds_read_b128 v[210:213], v209 offset:4096
	ds_read_b128 v[232:235], v209 offset:5120
	ds_read_b128 v[242:245], v209 offset:6144
	ds_read_b128 v[246:249], v209 offset:7168
	global_load_lds_dwordx4 v[190:191], off
	v_lshl_add_u64 v[190:191], s[40:41], 0, v[186:187]
	s_add_i32 m0, s67, 0xe000
	s_nop 0
	global_load_lds_dwordx4 v[190:191], off
	s_waitcnt vmcnt(8)
	s_waitcnt lgkmcnt(0)
	s_barrier
; #define PG8_STAGE(bufoff, gbase, voff) do { _Pragma("unroll") for (int _i = 0; _i < 2; ++_i) \
;         __builtin_amdgcn_global_load_lds((const unsigned*)((const char*)(gbase) + (voff)[_i]), (PG8_LAS unsigned*)(lds + (bufoff) + ldsw + _i * 8192), 16, 0, 0); } while (0)
; #define PG8_LDA(dst, b, h) do { _Pragma("unroll") for (int m = 0; m < 4; ++m) _Pragma("unroll") for (int k = 0; k < 2; ++k) dst[m][k] = *(const PG8_LAS bf16x8*)(lds + PG8_SA(b, h) + aoff + m * 2048 + k * 1024); } while (0)
; #define PG8_MMA(ai, bj, At, Bt) do { __builtin_amdgcn_s_setprio(1); _Pragma("unroll") for (int m = 0; m < 4; ++m) _Pragma("unroll") for (int n = 0; n < 2; ++n) _Pragma("unroll") for (int k = 0; k < 2; ++k) \
;         acc[ai][bj][m][n] = __builtin_amdgcn_mfma_f32_16x16x32_bf16(Bt[n][k], At[m][k], acc[ai][bj][m][n], 0, 0, 0); __builtin_amdgcn_s_setprio(0); } while (0)
; #define PG8_WAIT_V(n) asm volatile("s_waitcnt vmcnt(" #n ")" ::: "memory")
; #define PG8_WAIT_L(n) asm volatile("s_waitcnt lgkmcnt(" #n ")" ::: "memory")
; #define PG8_BAR __builtin_amdgcn_s_barrier()
; #define PG8_SCHED __builtin_amdgcn_sched_barrier(0)
; template <class Epi, class Sched, bool ALIGN_EPI = false, bool SP2 = false>
; __device__ __forceinline__ void gemm_phase(PG8_LAS unsigned char* lds, const Gemm g, const Sched& S, const Epi& E) {
;     ...
;             PG8_WAIT_V(8); PG8_WAIT_L(0); PG8_BAR; PG8_MMA(0, 0, At, B0); PG8_MMA(0, 1, At, B1); PG8_BAR; PG8_SCHED;
;             PG8_LDA(At, 0, 1); PG8_STAGE(PG8_SB(0, 0), b2, voffB); PG8_STAGE(PG8_SB(0, 1), b2 + hstep, voffB); PG8_STAGE(PG8_SA(0, 0), a2, voffA);
;             PG8_WAIT_V(8); PG8_WAIT_L(0); PG8_BAR; PG8_MMA(1, 0, At, B0); PG8_MMA(1, 1, At, B1); PG8_BAR; PG8_SCHED;
	v_mfma_f32_16x16x32_bf16 v[126:129], v[130:133], v[162:165], v[126:129]
	v_mfma_f32_16x16x32_bf16 v[122:125], v[138:141], v[162:165], v[122:125]
	v_mfma_f32_16x16x32_bf16 v[110:113], v[130:133], v[170:173], v[110:113]
	v_mfma_f32_16x16x32_bf16 v[106:109], v[138:141], v[170:173], v[106:109]
	v_mfma_f32_16x16x32_bf16 v[92:95], v[130:133], v[210:213], v[92:95]
	v_mfma_f32_16x16x32_bf16 v[88:91], v[138:141], v[210:213], v[88:91]
	v_mfma_f32_16x16x32_bf16 v[76:79], v[130:133], v[242:245], v[76:79]
	v_mfma_f32_16x16x32_bf16 v[72:75], v[138:141], v[242:245], v[72:75]
	v_mfma_f32_16x16x32_bf16 v[126:129], v[134:137], v[166:169], v[126:129]
	v_mfma_f32_16x16x32_bf16 v[122:125], v[142:145], v[166:169], v[122:125]
	v_mfma_f32_16x16x32_bf16 v[110:113], v[134:137], v[174:177], v[110:113]
	v_mfma_f32_16x16x32_bf16 v[106:109], v[142:145], v[174:177], v[106:109]
	v_mfma_f32_16x16x32_bf16 v[92:95], v[134:137], v[232:235], v[92:95]
	v_mfma_f32_16x16x32_bf16 v[88:91], v[142:145], v[232:235], v[88:91]
	v_mfma_f32_16x16x32_bf16 v[76:79], v[134:137], v[246:249], v[76:79]
	v_mfma_f32_16x16x32_bf16 v[72:75], v[142:145], v[246:249], v[72:75]
	v_mfma_f32_16x16x32_bf16 v[118:121], v[146:149], v[162:165], v[118:121]
	v_mfma_f32_16x16x32_bf16 v[114:117], v[154:157], v[162:165], v[114:117]
	v_mfma_f32_16x16x32_bf16 v[102:105], v[146:149], v[170:173], v[102:105]
	v_mfma_f32_16x16x32_bf16 v[98:101], v[154:157], v[170:173], v[98:101]
	v_mfma_f32_16x16x32_bf16 v[84:87], v[146:149], v[210:213], v[84:87]
	v_mfma_f32_16x16x32_bf16 v[80:83], v[154:157], v[210:213], v[80:83]
	v_mfma_f32_16x16x32_bf16 v[68:71], v[146:149], v[242:245], v[68:71]
	v_mfma_f32_16x16x32_bf16 v[64:67], v[154:157], v[242:245], v[64:67]
	v_mfma_f32_16x16x32_bf16 v[118:121], v[150:153], v[166:169], v[118:121]
	v_mfma_f32_16x16x32_bf16 v[114:117], v[158:161], v[166:169], v[114:117]
	v_mfma_f32_16x16x32_bf16 v[102:105], v[150:153], v[174:177], v[102:105]
	v_mfma_f32_16x16x32_bf16 v[98:101], v[158:161], v[174:177], v[98:101]
	v_mfma_f32_16x16x32_bf16 v[84:87], v[150:153], v[232:235], v[84:87]
	v_mfma_f32_16x16x32_bf16 v[80:83], v[158:161], v[232:235], v[80:83]
	v_mfma_f32_16x16x32_bf16 v[68:71], v[150:153], v[246:249], v[68:71]
	v_mfma_f32_16x16x32_bf16 v[64:67], v[158:161], v[246:249], v[64:67]
	s_barrier
	s_add_i32 s30, s30, s28
	v_lshl_add_u64 v[190:191], s[0:1], 0, v[96:97]
	s_mov_b32 m0, s30
	ds_read_b128 v[162:165], v209 offset:16384
	ds_read_b128 v[166:169], v209 offset:17408
	ds_read_b128 v[170:173], v209 offset:18432
	ds_read_b128 v[174:177], v209 offset:19456
	ds_read_b128 v[210:213], v209 offset:20480
	ds_read_b128 v[232:235], v209 offset:21504
	ds_read_b128 v[242:245], v209 offset:22528
	ds_read_b128 v[246:249], v209 offset:23552
	global_load_lds_dwordx4 v[190:191], off
	s_add_i32 m0, s30, 0x2000
	s_add_u32 s30, s0, 0x80000
	v_lshl_add_u64 v[204:205], s[0:1], 0, v[178:179]
	s_addc_u32 s31, s1, 0
	s_add_i32 s33, s33, s28
	global_load_lds_dwordx4 v[204:205], off
	v_lshl_add_u64 v[214:215], s[30:31], 0, v[96:97]
	s_mov_b32 m0, s33
	v_lshl_add_u64 v[228:229], s[4:5], 0, v[180:181]
	global_load_lds_dwordx4 v[214:215], off
	v_lshl_add_u64 v[214:215], s[30:31], 0, v[178:179]
	s_add_i32 m0, s33, 0x2000
	s_nop 0
	global_load_lds_dwordx4 v[214:215], off
	v_lshl_add_u64 v[214:215], s[4:5], 0, v[182:183]
	s_mov_b32 m0, s67
	s_nop 0
	global_load_lds_dwordx4 v[214:215], off
	s_mov_b32 m0, s68
	s_nop 0
	global_load_lds_dwordx4 v[228:229], off
	s_waitcnt vmcnt(8)
	s_waitcnt lgkmcnt(0)
	s_barrier
	v_mfma_f32_16x16x32_bf16 v[60:63], v[130:133], v[162:165], v[60:63]
	v_mfma_f32_16x16x32_bf16 v[56:59], v[138:141], v[162:165], v[56:59]
	v_mfma_f32_16x16x32_bf16 v[44:47], v[130:133], v[170:173], v[44:47]
	v_mfma_f32_16x16x32_bf16 v[40:43], v[138:141], v[170:173], v[40:43]
	v_mfma_f32_16x16x32_bf16 v[28:31], v[130:133], v[210:213], v[28:31]
	v_mfma_f32_16x16x32_bf16 v[24:27], v[138:141], v[210:213], v[24:27]
	v_mfma_f32_16x16x32_bf16 v[12:15], v[130:133], v[242:245], v[12:15]
	v_mfma_f32_16x16x32_bf16 v[8:11], v[138:141], v[242:245], v[8:11]
	v_mfma_f32_16x16x32_bf16 v[60:63], v[134:137], v[166:169], v[60:63]
	v_mfma_f32_16x16x32_bf16 v[56:59], v[142:145], v[166:169], v[56:59]
	v_mfma_f32_16x16x32_bf16 v[44:47], v[134:137], v[174:177], v[44:47]
	v_mfma_f32_16x16x32_bf16 v[40:43], v[142:145], v[174:177], v[40:43]
	v_mfma_f32_16x16x32_bf16 v[28:31], v[134:137], v[232:235], v[28:31]
	v_mfma_f32_16x16x32_bf16 v[24:27], v[142:145], v[232:235], v[24:27]
	v_mfma_f32_16x16x32_bf16 v[12:15], v[134:137], v[246:249], v[12:15]
	v_mfma_f32_16x16x32_bf16 v[8:11], v[142:145], v[246:249], v[8:11]
	v_mfma_f32_16x16x32_bf16 v[52:55], v[146:149], v[162:165], v[52:55]
	v_mfma_f32_16x16x32_bf16 v[48:51], v[154:157], v[162:165], v[48:51]
	v_mfma_f32_16x16x32_bf16 v[36:39], v[146:149], v[170:173], v[36:39]
	v_mfma_f32_16x16x32_bf16 v[32:35], v[154:157], v[170:173], v[32:35]
	v_mfma_f32_16x16x32_bf16 v[20:23], v[146:149], v[210:213], v[20:23]
	v_mfma_f32_16x16x32_bf16 v[16:19], v[154:157], v[210:213], v[16:19]
	v_mfma_f32_16x16x32_bf16 v[4:7], v[146:149], v[242:245], v[4:7]
	v_mfma_f32_16x16x32_bf16 v[0:3], v[154:157], v[242:245], v[0:3]
	v_mfma_f32_16x16x32_bf16 v[52:55], v[150:153], v[166:169], v[52:55]
	v_mfma_f32_16x16x32_bf16 v[48:51], v[158:161], v[166:169], v[48:51]
	v_mfma_f32_16x16x32_bf16 v[36:39], v[150:153], v[174:177], v[36:39]
	v_mfma_f32_16x16x32_bf16 v[32:35], v[158:161], v[174:177], v[32:35]
	v_mfma_f32_16x16x32_bf16 v[20:23], v[150:153], v[232:235], v[20:23]
	v_mfma_f32_16x16x32_bf16 v[16:19], v[158:161], v[232:235], v[16:19]
	v_mfma_f32_16x16x32_bf16 v[4:7], v[150:153], v[246:249], v[4:7]
	v_mfma_f32_16x16x32_bf16 v[0:3], v[158:161], v[246:249], v[0:3]
	s_barrier
; #define PG8_STAGE(bufoff, gbase, voff) do { _Pragma("unroll") for (int _i = 0; _i < 2; ++_i) \
;         __builtin_amdgcn_global_load_lds((const unsigned*)((const char*)(gbase) + (voff)[_i]), (PG8_LAS unsigned*)(lds + (bufoff) + ldsw + _i * 8192), 16, 0, 0); } while (0)
; #define PG8_LDA(dst, b, h) do { _Pragma("unroll") for (int m = 0; m < 4; ++m) _Pragma("unroll") for (int k = 0; k < 2; ++k) dst[m][k] = *(const PG8_LAS bf16x8*)(lds + PG8_SA(b, h) + aoff + m * 2048 + k * 1024); } while (0)
; #define PG8_LDB(dst, b, h) do { _Pragma("unroll") for (int n = 0; n < 2; ++n) _Pragma("unroll") for (int k = 0; k < 2; ++k) dst[n][k] = *(const PG8_LAS bf16x8*)(lds + PG8_SB(b, h) + boff + n * 2048 + k * 1024); } while (0)
; #define PG8_MMA(ai, bj, At, Bt) do { __builtin_amdgcn_s_setprio(1); _Pragma("unroll") for (int m = 0; m < 4; ++m) _Pragma("unroll") for (int n = 0; n < 2; ++n) _Pragma("unroll") for (int k = 0; k < 2; ++k) \
;         acc[ai][bj][m][n] = __builtin_amdgcn_mfma_f32_16x16x32_bf16(Bt[n][k], At[m][k], acc[ai][bj][m][n], 0, 0, 0); __builtin_amdgcn_s_setprio(0); } while (0)
; #define PG8_WAIT_V(n) asm volatile("s_waitcnt vmcnt(" #n ")" ::: "memory")
; #define PG8_WAIT_L(n) asm volatile("s_waitcnt lgkmcnt(" #n ")" ::: "memory")
; #define PG8_BAR __builtin_amdgcn_s_barrier()
; #define PG8_SCHED __builtin_amdgcn_sched_barrier(0)
; template <class Epi, class Sched, bool ALIGN_EPI = false, bool SP2 = false>
; __device__ __forceinline__ void gemm_phase(PG8_LAS unsigned char* lds, const Gemm g, const Sched& S, const Epi& E) {
;     ...
;             PG8_LDB(B0, 1, 0); PG8_LDB(B1, 1, 1); PG8_SCHED; PG8_LDA(At, 1, 0); PG8_STAGE(PG8_SA(0, 1), a2 + hstep, voffA);
;             PG8_WAIT_V(8); PG8_WAIT_L(0); PG8_BAR; PG8_MMA(0, 0, At, B0); PG8_MMA(0, 1, At, B1); PG8_BAR; PG8_SCHED;
	s_add_i32 s30, 0, 0x18000
	s_add_i32 s31, 0, 0x1c000
	v_add_u32_e32 v142, s30, v203
	v_add_u32_e32 v158, s31, v203
	ds_read_b128 v[130:133], v142
	ds_read_b128 v[134:137], v142 offset:1024
	ds_read_b128 v[138:141], v142 offset:2048
	ds_read_b128 v[142:145], v142 offset:3072
	ds_read_b128 v[146:149], v158
	ds_read_b128 v[150:153], v158 offset:1024
	ds_read_b128 v[154:157], v158 offset:2048
	ds_read_b128 v[158:161], v158 offset:3072
	s_add_u32 s4, s4, 0x80000
	s_addc_u32 s5, s5, 0
	s_mov_b32 m0, s69
	v_lshl_add_u64 v[230:231], s[4:5], 0, v[182:183]
	ds_read_b128 v[162:165], v209 offset:32768
	ds_read_b128 v[166:169], v209 offset:33792
	ds_read_b128 v[170:173], v209 offset:34816
	ds_read_b128 v[174:177], v209 offset:35840
	ds_read_b128 v[210:213], v209 offset:36864
	ds_read_b128 v[232:235], v209 offset:37888
	ds_read_b128 v[242:245], v209 offset:38912
	ds_read_b128 v[246:249], v209 offset:39936
	global_load_lds_dwordx4 v[230:231], off
	v_lshl_add_u64 v[230:231], s[4:5], 0, v[180:181]
	s_mov_b32 m0, s72
	s_nop 0
	global_load_lds_dwordx4 v[230:231], off
	s_waitcnt vmcnt(8)
	s_waitcnt lgkmcnt(0)
	s_barrier
	v_mfma_f32_16x16x32_bf16 v[126:129], v[130:133], v[162:165], v[126:129]
	v_mfma_f32_16x16x32_bf16 v[122:125], v[138:141], v[162:165], v[122:125]
	v_mfma_f32_16x16x32_bf16 v[110:113], v[130:133], v[170:173], v[110:113]
	v_mfma_f32_16x16x32_bf16 v[106:109], v[138:141], v[170:173], v[106:109]
	v_mfma_f32_16x16x32_bf16 v[92:95], v[130:133], v[210:213], v[92:95]
	v_mfma_f32_16x16x32_bf16 v[88:91], v[138:141], v[210:213], v[88:91]
	v_mfma_f32_16x16x32_bf16 v[76:79], v[130:133], v[242:245], v[76:79]
	v_mfma_f32_16x16x32_bf16 v[72:75], v[138:141], v[242:245], v[72:75]
	v_mfma_f32_16x16x32_bf16 v[126:129], v[134:137], v[166:169], v[126:129]
	v_mfma_f32_16x16x32_bf16 v[122:125], v[142:145], v[166:169], v[122:125]
	v_mfma_f32_16x16x32_bf16 v[110:113], v[134:137], v[174:177], v[110:113]
	v_mfma_f32_16x16x32_bf16 v[106:109], v[142:145], v[174:177], v[106:109]
	v_mfma_f32_16x16x32_bf16 v[92:95], v[134:137], v[232:235], v[92:95]
	v_mfma_f32_16x16x32_bf16 v[88:91], v[142:145], v[232:235], v[88:91]
	v_mfma_f32_16x16x32_bf16 v[76:79], v[134:137], v[246:249], v[76:79]
	v_mfma_f32_16x16x32_bf16 v[72:75], v[142:145], v[246:249], v[72:75]
	v_mfma_f32_16x16x32_bf16 v[118:121], v[146:149], v[162:165], v[118:121]
	v_mfma_f32_16x16x32_bf16 v[114:117], v[154:157], v[162:165], v[114:117]
	v_mfma_f32_16x16x32_bf16 v[102:105], v[146:149], v[170:173], v[102:105]
	v_mfma_f32_16x16x32_bf16 v[98:101], v[154:157], v[170:173], v[98:101]
	v_mfma_f32_16x16x32_bf16 v[84:87], v[146:149], v[210:213], v[84:87]
	v_mfma_f32_16x16x32_bf16 v[80:83], v[154:157], v[210:213], v[80:83]
	v_mfma_f32_16x16x32_bf16 v[68:71], v[146:149], v[242:245], v[68:71]
	v_mfma_f32_16x16x32_bf16 v[64:67], v[154:157], v[242:245], v[64:67]
	v_mfma_f32_16x16x32_bf16 v[118:121], v[150:153], v[166:169], v[118:121]
	v_mfma_f32_16x16x32_bf16 v[114:117], v[158:161], v[166:169], v[114:117]
	v_mfma_f32_16x16x32_bf16 v[102:105], v[150:153], v[174:177], v[102:105]
	v_mfma_f32_16x16x32_bf16 v[98:101], v[158:161], v[174:177], v[98:101]
	v_mfma_f32_16x16x32_bf16 v[84:87], v[150:153], v[232:235], v[84:87]
	v_mfma_f32_16x16x32_bf16 v[80:83], v[158:161], v[232:235], v[80:83]
	v_mfma_f32_16x16x32_bf16 v[68:71], v[150:153], v[246:249], v[68:71]
	v_mfma_f32_16x16x32_bf16 v[64:67], v[158:161], v[246:249], v[64:67]
	s_barrier
; #define PG8_STAGE(bufoff, gbase, voff) do { _Pragma("unroll") for (int _i = 0; _i < 2; ++_i) \
;         __builtin_amdgcn_global_load_lds((const unsigned*)((const char*)(gbase) + (voff)[_i]), (PG8_LAS unsigned*)(lds + (bufoff) + ldsw + _i * 8192), 16, 0, 0); } while (0)
; #define PG8_LDA(dst, b, h) do { _Pragma("unroll") for (int m = 0; m < 4; ++m) _Pragma("unroll") for (int k = 0; k < 2; ++k) dst[m][k] = *(const PG8_LAS bf16x8*)(lds + PG8_SA(b, h) + aoff + m * 2048 + k * 1024); } while (0)
; #define PG8_MMA(ai, bj, At, Bt) do { __builtin_amdgcn_s_setprio(1); _Pragma("unroll") for (int m = 0; m < 4; ++m) _Pragma("unroll") for (int n = 0; n < 2; ++n) _Pragma("unroll") for (int k = 0; k < 2; ++k) \
;         acc[ai][bj][m][n] = __builtin_amdgcn_mfma_f32_16x16x32_bf16(Bt[n][k], At[m][k], acc[ai][bj][m][n], 0, 0, 0); __builtin_amdgcn_s_setprio(0); } while (0)
; #define PG8_WAIT_V(n) asm volatile("s_waitcnt vmcnt(" #n ")" ::: "memory")
; #define PG8_WAIT_L(n) asm volatile("s_waitcnt lgkmcnt(" #n ")" ::: "memory")
; #define PG8_BAR __builtin_amdgcn_s_barrier()
; #define PG8_SCHED __builtin_amdgcn_sched_barrier(0)
; template <class Epi, class Sched, bool ALIGN_EPI = false, bool SP2 = false>
; __device__ __forceinline__ void gemm_phase(PG8_LAS unsigned char* lds, const Gemm g, const Sched& S, const Epi& E) {
;     ...
;             PG8_LDA(At, 1, 1); PG8_STAGE(PG8_SB(1, 0), b3, voffB); PG8_STAGE(PG8_SB(1, 1), b3 + hstep, voffB); PG8_STAGE(PG8_SA(1, 0), a3, voffA);
;             PG8_WAIT_V(8); PG8_WAIT_L(0); PG8_BAR; PG8_MMA(1, 0, At, B0); PG8_MMA(1, 1, At, B1); PG8_BAR; PG8_SCHED;
	s_add_i32 s4, s30, s28
	v_lshl_add_u64 v[190:191], v[190:191], 0, s[20:21]
	s_mov_b32 m0, s4
	ds_read_b128 v[162:165], v209 offset:49152
	ds_read_b128 v[166:169], v209 offset:50176
	ds_read_b128 v[170:173], v209 offset:51200
	ds_read_b128 v[174:177], v209 offset:52224
	ds_read_b128 v[210:213], v209 offset:53248
	ds_read_b128 v[232:235], v209 offset:54272
	ds_read_b128 v[242:245], v209 offset:55296
	ds_read_b128 v[246:249], v209 offset:56320
	global_load_lds_dwordx4 v[190:191], off
	s_add_i32 m0, s4, 0x2000
	s_add_u32 s0, s0, 0x80080
	v_lshl_add_u64 v[190:191], v[204:205], 0, s[20:21]
	s_addc_u32 s1, s1, 0
	s_add_i32 s4, s31, s28
	global_load_lds_dwordx4 v[190:191], off
	v_lshl_add_u64 v[190:191], s[0:1], 0, v[96:97]
	s_mov_b32 m0, s4
	s_nop 0
	global_load_lds_dwordx4 v[190:191], off
	v_lshl_add_u64 v[190:191], s[0:1], 0, v[178:179]
	s_add_i32 m0, s4, 0x2000
	s_nop 0
	global_load_lds_dwordx4 v[190:191], off
	v_lshl_add_u64 v[190:191], v[214:215], 0, s[20:21]
	s_mov_b32 m0, s74
	s_nop 0
	global_load_lds_dwordx4 v[190:191], off
	v_lshl_add_u64 v[190:191], v[228:229], 0, s[20:21]
	s_mov_b32 m0, s75
	s_nop 0
	global_load_lds_dwordx4 v[190:191], off
	s_waitcnt vmcnt(8)
	s_waitcnt lgkmcnt(0)
	s_barrier
	v_mfma_f32_16x16x32_bf16 v[60:63], v[130:133], v[162:165], v[60:63]
	v_mfma_f32_16x16x32_bf16 v[56:59], v[138:141], v[162:165], v[56:59]
	v_mfma_f32_16x16x32_bf16 v[44:47], v[130:133], v[170:173], v[44:47]
	v_mfma_f32_16x16x32_bf16 v[40:43], v[138:141], v[170:173], v[40:43]
	v_mfma_f32_16x16x32_bf16 v[28:31], v[130:133], v[210:213], v[28:31]
	v_mfma_f32_16x16x32_bf16 v[24:27], v[138:141], v[210:213], v[24:27]
	v_mfma_f32_16x16x32_bf16 v[12:15], v[130:133], v[242:245], v[12:15]
	v_mfma_f32_16x16x32_bf16 v[8:11], v[138:141], v[242:245], v[8:11]
	v_mfma_f32_16x16x32_bf16 v[60:63], v[134:137], v[166:169], v[60:63]
	v_mfma_f32_16x16x32_bf16 v[56:59], v[142:145], v[166:169], v[56:59]
	v_mfma_f32_16x16x32_bf16 v[44:47], v[134:137], v[174:177], v[44:47]
	v_mfma_f32_16x16x32_bf16 v[40:43], v[142:145], v[174:177], v[40:43]
	v_mfma_f32_16x16x32_bf16 v[28:31], v[134:137], v[232:235], v[28:31]
	v_mfma_f32_16x16x32_bf16 v[24:27], v[142:145], v[232:235], v[24:27]
	v_mfma_f32_16x16x32_bf16 v[12:15], v[134:137], v[246:249], v[12:15]
	v_mfma_f32_16x16x32_bf16 v[8:11], v[142:145], v[246:249], v[8:11]
	v_mfma_f32_16x16x32_bf16 v[52:55], v[146:149], v[162:165], v[52:55]
	v_mfma_f32_16x16x32_bf16 v[48:51], v[154:157], v[162:165], v[48:51]
	v_mfma_f32_16x16x32_bf16 v[36:39], v[146:149], v[170:173], v[36:39]
	v_mfma_f32_16x16x32_bf16 v[32:35], v[154:157], v[170:173], v[32:35]
	v_mfma_f32_16x16x32_bf16 v[20:23], v[146:149], v[210:213], v[20:23]
	v_mfma_f32_16x16x32_bf16 v[16:19], v[154:157], v[210:213], v[16:19]
	v_mfma_f32_16x16x32_bf16 v[4:7], v[146:149], v[242:245], v[4:7]
	v_mfma_f32_16x16x32_bf16 v[0:3], v[154:157], v[242:245], v[0:3]
	v_mfma_f32_16x16x32_bf16 v[52:55], v[150:153], v[166:169], v[52:55]
	v_mfma_f32_16x16x32_bf16 v[48:51], v[158:161], v[166:169], v[48:51]
	v_mfma_f32_16x16x32_bf16 v[36:39], v[150:153], v[174:177], v[36:39]
	v_mfma_f32_16x16x32_bf16 v[32:35], v[158:161], v[174:177], v[32:35]
	v_mfma_f32_16x16x32_bf16 v[20:23], v[150:153], v[232:235], v[20:23]
	v_mfma_f32_16x16x32_bf16 v[16:19], v[158:161], v[232:235], v[16:19]
	v_mfma_f32_16x16x32_bf16 v[4:7], v[150:153], v[246:249], v[4:7]
	v_mfma_f32_16x16x32_bf16 v[0:3], v[158:161], v[246:249], v[0:3]
	s_barrier
	s_add_i32 s19, s19, 2
	s_add_u32 s15, s15, 0x100
	s_addc_u32 s17, s17, 0
	s_add_u32 s40, s40, 0x100
	s_addc_u32 s41, s41, 0
	s_cmp_gt_u32 s19, 29
	s_cbranch_scc0 .LBB0_417
	s_and_b64 vcc, exec, s[34:35]
	s_cbranch_vccz .LBB0_420
	s_barrier

; #define PG8_STAGE(bufoff, gbase, voff) do { _Pragma("unroll") for (int _i = 0; _i < 2; ++_i) \
;         __builtin_amdgcn_global_load_lds((const unsigned*)((const char*)(gbase) + (voff)[_i]), (PG8_LAS unsigned*)(lds + (bufoff) + ldsw + _i * 8192), 16, 0, 0); } while (0)
; #define PG8_LDA(dst, b, h) do { _Pragma("unroll") for (int m = 0; m < 4; ++m) _Pragma("unroll") for (int k = 0; k < 2; ++k) dst[m][k] = *(const PG8_LAS bf16x8*)(lds + PG8_SA(b, h) + aoff + m * 2048 + k * 1024); } while (0)
; #define PG8_LDB(dst, b, h) do { _Pragma("unroll") for (int n = 0; n < 2; ++n) _Pragma("unroll") for (int k = 0; k < 2; ++k) dst[n][k] = *(const PG8_LAS bf16x8*)(lds + PG8_SB(b, h) + boff + n * 2048 + k * 1024); } while (0)
; #define PG8_MMA(ai, bj, At, Bt) do { __builtin_amdgcn_s_setprio(1); _Pragma("unroll") for (int m = 0; m < 4; ++m) _Pragma("unroll") for (int n = 0; n < 2; ++n) _Pragma("unroll") for (int k = 0; k < 2; ++k) \
;         acc[ai][bj][m][n] = __builtin_amdgcn_mfma_f32_16x16x32_bf16(Bt[n][k], At[m][k], acc[ai][bj][m][n], 0, 0, 0); __builtin_amdgcn_s_setprio(0); } while (0)
; #define PG8_WAIT_V(n) asm volatile("s_waitcnt vmcnt(" #n ")" ::: "memory")
; #define PG8_WAIT_L(n) asm volatile("s_waitcnt lgkmcnt(" #n ")" ::: "memory")
; template <class Epi, class Sched, bool ALIGN_EPI = false, bool SP2 = false>
; __device__ __forceinline__ void gemm_phase(PG8_LAS unsigned char* lds, const Gemm g, const Sched& S, const Epi& E) {
;     ...
;             const bool last = (t == nt - 2);
;             const char* a1 = cA + (size_t)(t + 1) * kstep;
;             const char* a2 = last ? nA : cA + (size_t)(t + 2) * kstep; const char* b2 = last ? nB : cB + (size_t)(t + 2) * kstep;
;             const char* a3 = a2 + kstep; const char* b3 = b2 + kstep;
;             if (last && has_next) S.a_ready(nxt);
;             if constexpr (SP2) {
;             PG8_LDB(B0, 0, 0); PG8_LDB(B1, 0, 1); PG8_SCHED; PG8_LDA(At, 0, 0); PG8_STAGE(PG8_SA(1, 1), a1 + hstep, voffA);
;             PG8_WAIT_V(8); PG8_WAIT_L(0); PG8_BAR; PG8_MMA(0, 0, At, B0); PG8_MMA(0, 1, At, B1); PG8_BAR; PG8_SCHED;
;     ...
;         for (int a = 0; a < 2; ++a)
; #pragma unroll
;             for (int b = 0; b < 2; ++b)
; #pragma unroll
;                 for (int m = 0; m < 4; ++m)
; #pragma unroll
;                     for (int n = 0; n < 2; ++n) acc[a][b][m][n] = (f32x4){0.f, 0.f, 0.f, 0.f};
.LBB0_446:
	s_add_u32 s17, s66, 0x100
	s_addc_u32 s23, s67, 0
	s_add_u32 s66, s68, 0x80
	v_mov_b32_e32 v0, 0
	s_addc_u32 s67, s69, 0
	s_mov_b32 s0, 0
	s_waitcnt lgkmcnt(0)
	v_mov_b32_e32 v1, v0
	v_mov_b32_e32 v2, v0
	v_mov_b32_e32 v3, v0
	v_mov_b32_e32 v4, v0
	v_mov_b32_e32 v5, v0
	v_mov_b32_e32 v6, v0
	v_mov_b32_e32 v7, v0
	v_mov_b32_e32 v16, v0
	v_mov_b32_e32 v17, v0
	v_mov_b32_e32 v18, v0
	v_mov_b32_e32 v19, v0
	v_mov_b32_e32 v20, v0
	v_mov_b32_e32 v21, v0
	v_mov_b32_e32 v22, v0
	v_mov_b32_e32 v23, v0
	v_mov_b32_e32 v32, v0
	v_mov_b32_e32 v33, v0
	v_mov_b32_e32 v34, v0
	v_mov_b32_e32 v35, v0
	v_mov_b32_e32 v36, v0
	v_mov_b32_e32 v37, v0
	v_mov_b32_e32 v38, v0
	v_mov_b32_e32 v39, v0
	v_mov_b32_e32 v48, v0
	v_mov_b32_e32 v49, v0
	v_mov_b32_e32 v50, v0
	v_mov_b32_e32 v51, v0
	v_mov_b32_e32 v52, v0
	v_mov_b32_e32 v53, v0
	v_mov_b32_e32 v54, v0
	v_mov_b32_e32 v55, v0
	v_mov_b32_e32 v8, v0
	v_mov_b32_e32 v9, v0
	v_mov_b32_e32 v10, v0
	v_mov_b32_e32 v11, v0
	v_mov_b32_e32 v12, v0
	v_mov_b32_e32 v13, v0
	v_mov_b32_e32 v14, v0
	v_mov_b32_e32 v15, v0
	v_mov_b32_e32 v24, v0
	v_mov_b32_e32 v25, v0
	v_mov_b32_e32 v26, v0
	v_mov_b32_e32 v27, v0
	v_mov_b32_e32 v28, v0
	v_mov_b32_e32 v29, v0
	v_mov_b32_e32 v30, v0
	v_mov_b32_e32 v31, v0
	v_mov_b32_e32 v40, v0
	v_mov_b32_e32 v41, v0
	v_mov_b32_e32 v42, v0
	v_mov_b32_e32 v43, v0
	v_mov_b32_e32 v44, v0
	v_mov_b32_e32 v45, v0
	v_mov_b32_e32 v46, v0
	v_mov_b32_e32 v47, v0
	v_mov_b32_e32 v56, v0
	v_mov_b32_e32 v57, v0
	v_mov_b32_e32 v58, v0
	v_mov_b32_e32 v59, v0
	v_mov_b32_e32 v60, v0
	v_mov_b32_e32 v61, v0
	v_mov_b32_e32 v62, v0
	v_mov_b32_e32 v63, v0
	v_mov_b32_e32 v64, v0
	v_mov_b32_e32 v65, v0
	v_mov_b32_e32 v66, v0
	v_mov_b32_e32 v67, v0
	v_mov_b32_e32 v68, v0
	v_mov_b32_e32 v69, v0
	v_mov_b32_e32 v70, v0
	v_mov_b32_e32 v71, v0
	v_mov_b32_e32 v80, v0
	v_mov_b32_e32 v81, v0
	v_mov_b32_e32 v82, v0
	v_mov_b32_e32 v83, v0
	v_mov_b32_e32 v84, v0
	v_mov_b32_e32 v85, v0
	v_mov_b32_e32 v86, v0
	v_mov_b32_e32 v87, v0
	v_mov_b32_e32 v102, v0
	v_mov_b32_e32 v103, v0
	v_mov_b32_e32 v104, v0
	v_mov_b32_e32 v105, v0
	v_mov_b32_e32 v110, v0
	v_mov_b32_e32 v111, v0
	v_mov_b32_e32 v112, v0
	v_mov_b32_e32 v113, v0
	v_mov_b32_e32 v130, v0
	v_mov_b32_e32 v131, v0
	v_mov_b32_e32 v132, v0
	v_mov_b32_e32 v133, v0
	v_mov_b32_e32 v134, v0
	v_mov_b32_e32 v135, v0
	v_mov_b32_e32 v136, v0
	v_mov_b32_e32 v137, v0
	v_mov_b32_e32 v72, v0
	v_mov_b32_e32 v73, v0
	v_mov_b32_e32 v74, v0
	v_mov_b32_e32 v75, v0
	v_mov_b32_e32 v76, v0
	v_mov_b32_e32 v77, v0
	v_mov_b32_e32 v78, v0
	v_mov_b32_e32 v79, v0
	v_mov_b32_e32 v88, v0
	v_mov_b32_e32 v89, v0
	v_mov_b32_e32 v90, v0
	v_mov_b32_e32 v91, v0
	v_mov_b32_e32 v92, v0
	v_mov_b32_e32 v93, v0
	v_mov_b32_e32 v94, v0
	v_mov_b32_e32 v95, v0
	v_mov_b32_e32 v114, v0
	v_mov_b32_e32 v115, v0
	v_mov_b32_e32 v116, v0
	v_mov_b32_e32 v117, v0
	v_mov_b32_e32 v122, v0
	v_mov_b32_e32 v123, v0
	v_mov_b32_e32 v124, v0
	v_mov_b32_e32 v125, v0
	v_mov_b32_e32 v146, v0
	v_mov_b32_e32 v147, v0
	v_mov_b32_e32 v148, v0
	v_mov_b32_e32 v149, v0
	v_mov_b32_e32 v154, v0
	v_mov_b32_e32 v155, v0
	v_mov_b32_e32 v156, v0
	v_mov_b32_e32 v157, v0
	s_cmp_lg_u64 s[62:63], 0
	s_cbranch_scc1 .Lgp_b
	s_setprio 1
.Lgp_b:
.LBB0_447:
	s_add_i32 s28, s0, 2
	s_add_u32 s30, s66, 0x80
	s_addc_u32 s1, s67, 0
	s_add_i32 s33, 0, 0x10000
	s_cmp_eq_u32 s59, s0
	s_cselect_b32 s1, s43, s1
	s_cselect_b32 s0, s42, s30
	s_cselect_b32 s31, s65, s23
	s_cselect_b32 s30, s64, s17
	s_add_i32 s52, 0, 0x14000
	v_add_u32_e32 v126, s33, v232
	v_add_u32_e32 v158, s52, v232
	ds_read_b128 v[98:101], v126
	ds_read_b128 v[106:109], v126 offset:1024
	ds_read_b128 v[118:121], v126 offset:2048
	ds_read_b128 v[126:129], v126 offset:3072
	ds_read_b128 v[138:141], v158
	ds_read_b128 v[142:145], v158 offset:1024
	ds_read_b128 v[150:153], v158 offset:2048
	ds_read_b128 v[158:161], v158 offset:3072
	v_lshl_add_u64 v[212:213], s[66:67], 0, v[210:211]
	s_add_i32 m0, s4, 0xc000
	ds_read_b128 v[162:165], v234
	ds_read_b128 v[166:169], v234 offset:1024
	ds_read_b128 v[170:173], v234 offset:2048
	ds_read_b128 v[174:177], v234 offset:3072
	ds_read_b128 v[178:181], v234 offset:4096
	ds_read_b128 v[182:185], v234 offset:5120
	ds_read_b128 v[186:189], v234 offset:6144
	ds_read_b128 v[190:193], v234 offset:7168
	global_load_lds_dwordx4 v[212:213], off
	v_lshl_add_u64 v[212:213], s[66:67], 0, v[208:209]
	s_add_i32 m0, s4, 0xe000
	s_nop 0
	global_load_lds_dwordx4 v[212:213], off
	s_waitcnt vmcnt(8)
	s_waitcnt lgkmcnt(0)
	s_barrier
	v_mfma_f32_16x16x32_bf16 v[154:157], v[98:101], v[162:165], v[154:157]
	v_mfma_f32_16x16x32_bf16 v[146:149], v[118:121], v[162:165], v[146:149]
	v_mfma_f32_16x16x32_bf16 v[122:125], v[98:101], v[170:173], v[122:125]
	v_mfma_f32_16x16x32_bf16 v[114:117], v[118:121], v[170:173], v[114:117]
	v_mfma_f32_16x16x32_bf16 v[92:95], v[98:101], v[178:181], v[92:95]
	v_mfma_f32_16x16x32_bf16 v[88:91], v[118:121], v[178:181], v[88:91]
	v_mfma_f32_16x16x32_bf16 v[76:79], v[98:101], v[186:189], v[76:79]
	v_mfma_f32_16x16x32_bf16 v[72:75], v[118:121], v[186:189], v[72:75]
	v_mfma_f32_16x16x32_bf16 v[154:157], v[106:109], v[166:169], v[154:157]
	v_mfma_f32_16x16x32_bf16 v[146:149], v[126:129], v[166:169], v[146:149]
	v_mfma_f32_16x16x32_bf16 v[122:125], v[106:109], v[174:177], v[122:125]
	v_mfma_f32_16x16x32_bf16 v[114:117], v[126:129], v[174:177], v[114:117]
	v_mfma_f32_16x16x32_bf16 v[92:95], v[106:109], v[182:185], v[92:95]
	v_mfma_f32_16x16x32_bf16 v[88:91], v[126:129], v[182:185], v[88:91]
	v_mfma_f32_16x16x32_bf16 v[76:79], v[106:109], v[190:193], v[76:79]
	v_mfma_f32_16x16x32_bf16 v[72:75], v[126:129], v[190:193], v[72:75]
	v_mfma_f32_16x16x32_bf16 v[134:137], v[138:141], v[162:165], v[134:137]
	v_mfma_f32_16x16x32_bf16 v[130:133], v[150:153], v[162:165], v[130:133]
	v_mfma_f32_16x16x32_bf16 v[110:113], v[138:141], v[170:173], v[110:113]
	v_mfma_f32_16x16x32_bf16 v[102:105], v[150:153], v[170:173], v[102:105]
	v_mfma_f32_16x16x32_bf16 v[84:87], v[138:141], v[178:181], v[84:87]
	v_mfma_f32_16x16x32_bf16 v[80:83], v[150:153], v[178:181], v[80:83]
	v_mfma_f32_16x16x32_bf16 v[68:71], v[138:141], v[186:189], v[68:71]
	v_mfma_f32_16x16x32_bf16 v[64:67], v[150:153], v[186:189], v[64:67]
	v_mfma_f32_16x16x32_bf16 v[134:137], v[142:145], v[166:169], v[134:137]
	v_mfma_f32_16x16x32_bf16 v[130:133], v[158:161], v[166:169], v[130:133]
	v_mfma_f32_16x16x32_bf16 v[110:113], v[142:145], v[174:177], v[110:113]
	v_mfma_f32_16x16x32_bf16 v[102:105], v[158:161], v[174:177], v[102:105]
	v_mfma_f32_16x16x32_bf16 v[84:87], v[142:145], v[182:185], v[84:87]
	v_mfma_f32_16x16x32_bf16 v[80:83], v[158:161], v[182:185], v[80:83]
	v_mfma_f32_16x16x32_bf16 v[68:71], v[142:145], v[190:193], v[68:71]
	v_mfma_f32_16x16x32_bf16 v[64:67], v[158:161], v[190:193], v[64:67]
	s_barrier
; #define PG8_STAGE(bufoff, gbase, voff) do { _Pragma("unroll") for (int _i = 0; _i < 2; ++_i) \
;         __builtin_amdgcn_global_load_lds((const unsigned*)((const char*)(gbase) + (voff)[_i]), (PG8_LAS unsigned*)(lds + (bufoff) + ldsw + _i * 8192), 16, 0, 0); } while (0)
; #define PG8_LDA(dst, b, h) do { _Pragma("unroll") for (int m = 0; m < 4; ++m) _Pragma("unroll") for (int k = 0; k < 2; ++k) dst[m][k] = *(const PG8_LAS bf16x8*)(lds + PG8_SA(b, h) + aoff + m * 2048 + k * 1024); } while (0)
; #define PG8_LDB(dst, b, h) do { _Pragma("unroll") for (int n = 0; n < 2; ++n) _Pragma("unroll") for (int k = 0; k < 2; ++k) dst[n][k] = *(const PG8_LAS bf16x8*)(lds + PG8_SB(b, h) + boff + n * 2048 + k * 1024); } while (0)
; #define PG8_MMA(ai, bj, At, Bt) do { __builtin_amdgcn_s_setprio(1); _Pragma("unroll") for (int m = 0; m < 4; ++m) _Pragma("unroll") for (int n = 0; n < 2; ++n) _Pragma("unroll") for (int k = 0; k < 2; ++k) \
;         acc[ai][bj][m][n] = __builtin_amdgcn_mfma_f32_16x16x32_bf16(Bt[n][k], At[m][k], acc[ai][bj][m][n], 0, 0, 0); __builtin_amdgcn_s_setprio(0); } while (0)
; #define PG8_WAIT_V(n) asm volatile("s_waitcnt vmcnt(" #n ")" ::: "memory")
; #define PG8_WAIT_L(n) asm volatile("s_waitcnt lgkmcnt(" #n ")" ::: "memory")
; #define PG8_BAR __builtin_amdgcn_s_barrier()
; #define PG8_SCHED __builtin_amdgcn_sched_barrier(0)
; template <class Epi, class Sched, bool ALIGN_EPI = false, bool SP2 = false>
; __device__ __forceinline__ void gemm_phase(PG8_LAS unsigned char* lds, const Gemm g, const Sched& S, const Epi& E) {
;     ...
;             PG8_LDA(At, 0, 1); PG8_STAGE(PG8_SB(0, 0), b2, voffB); PG8_STAGE(PG8_SB(0, 1), b2 + hstep, voffB); PG8_STAGE(PG8_SA(0, 0), a2, voffA);
;             PG8_WAIT_V(8); PG8_WAIT_L(0); PG8_BAR; PG8_MMA(1, 0, At, B0); PG8_MMA(1, 1, At, B1); PG8_BAR; PG8_SCHED;
;             PG8_LDB(B0, 1, 0); PG8_LDB(B1, 1, 1); PG8_SCHED; PG8_LDA(At, 1, 0); PG8_STAGE(PG8_SA(0, 1), a2 + hstep, voffA);
;             PG8_WAIT_V(8); PG8_WAIT_L(0); PG8_BAR; PG8_MMA(0, 0, At, B0); PG8_MMA(0, 1, At, B1); PG8_BAR; PG8_SCHED;
	s_add_i32 s33, s33, s2
	v_lshl_add_u64 v[212:213], s[30:31], 0, v[96:97]
	s_mov_b32 m0, s33
	ds_read_b128 v[162:165], v234 offset:16384
	ds_read_b128 v[166:169], v234 offset:17408
	ds_read_b128 v[170:173], v234 offset:18432
	ds_read_b128 v[174:177], v234 offset:19456
	ds_read_b128 v[178:181], v234 offset:20480
	ds_read_b128 v[182:185], v234 offset:21504
	ds_read_b128 v[186:189], v234 offset:22528
	ds_read_b128 v[190:193], v234 offset:23552
	global_load_lds_dwordx4 v[212:213], off
	s_add_i32 m0, s33, 0x2000
	v_lshl_add_u64 v[214:215], s[30:31], 0, v[202:203]
	s_add_u32 s30, s30, s22
	s_addc_u32 s31, s31, 0
	s_add_i32 s33, s52, s2
	global_load_lds_dwordx4 v[214:215], off
	v_lshl_add_u64 v[228:229], s[30:31], 0, v[96:97]
	s_mov_b32 m0, s33
	v_lshl_add_u64 v[236:237], s[30:31], 0, v[202:203]
	global_load_lds_dwordx4 v[228:229], off
	s_add_i32 m0, s33, 0x2000
	v_lshl_add_u64 v[242:243], s[0:1], 0, v[206:207]
	global_load_lds_dwordx4 v[236:237], off
	s_mov_b32 m0, s4
	v_lshl_add_u64 v[244:245], s[0:1], 0, v[204:205]
	global_load_lds_dwordx4 v[242:243], off
	s_mov_b32 m0, s5
	s_nop 0
	global_load_lds_dwordx4 v[244:245], off
	s_waitcnt vmcnt(8)
	s_waitcnt lgkmcnt(0)
	s_barrier
	v_mfma_f32_16x16x32_bf16 v[60:63], v[98:101], v[162:165], v[60:63]
	v_mfma_f32_16x16x32_bf16 v[56:59], v[118:121], v[162:165], v[56:59]
	v_mfma_f32_16x16x32_bf16 v[44:47], v[98:101], v[170:173], v[44:47]
	v_mfma_f32_16x16x32_bf16 v[40:43], v[118:121], v[170:173], v[40:43]
	v_mfma_f32_16x16x32_bf16 v[28:31], v[98:101], v[178:181], v[28:31]
	v_mfma_f32_16x16x32_bf16 v[24:27], v[118:121], v[178:181], v[24:27]
	v_mfma_f32_16x16x32_bf16 v[12:15], v[98:101], v[186:189], v[12:15]
	v_mfma_f32_16x16x32_bf16 v[8:11], v[118:121], v[186:189], v[8:11]
	v_mfma_f32_16x16x32_bf16 v[60:63], v[106:109], v[166:169], v[60:63]
	v_mfma_f32_16x16x32_bf16 v[56:59], v[126:129], v[166:169], v[56:59]
	v_mfma_f32_16x16x32_bf16 v[44:47], v[106:109], v[174:177], v[44:47]
	v_mfma_f32_16x16x32_bf16 v[40:43], v[126:129], v[174:177], v[40:43]
	v_mfma_f32_16x16x32_bf16 v[28:31], v[106:109], v[182:185], v[28:31]
	v_mfma_f32_16x16x32_bf16 v[24:27], v[126:129], v[182:185], v[24:27]
	v_mfma_f32_16x16x32_bf16 v[12:15], v[106:109], v[190:193], v[12:15]
	v_mfma_f32_16x16x32_bf16 v[8:11], v[126:129], v[190:193], v[8:11]
	v_mfma_f32_16x16x32_bf16 v[52:55], v[138:141], v[162:165], v[52:55]
	v_mfma_f32_16x16x32_bf16 v[48:51], v[150:153], v[162:165], v[48:51]
	v_mfma_f32_16x16x32_bf16 v[36:39], v[138:141], v[170:173], v[36:39]
	v_mfma_f32_16x16x32_bf16 v[32:35], v[150:153], v[170:173], v[32:35]
	v_mfma_f32_16x16x32_bf16 v[20:23], v[138:141], v[178:181], v[20:23]
	v_mfma_f32_16x16x32_bf16 v[16:19], v[150:153], v[178:181], v[16:19]
	v_mfma_f32_16x16x32_bf16 v[4:7], v[138:141], v[186:189], v[4:7]
	v_mfma_f32_16x16x32_bf16 v[0:3], v[150:153], v[186:189], v[0:3]
	v_mfma_f32_16x16x32_bf16 v[52:55], v[142:145], v[166:169], v[52:55]
	v_mfma_f32_16x16x32_bf16 v[48:51], v[158:161], v[166:169], v[48:51]
	v_mfma_f32_16x16x32_bf16 v[36:39], v[142:145], v[174:177], v[36:39]
	v_mfma_f32_16x16x32_bf16 v[32:35], v[158:161], v[174:177], v[32:35]
	v_mfma_f32_16x16x32_bf16 v[20:23], v[142:145], v[182:185], v[20:23]
	v_mfma_f32_16x16x32_bf16 v[16:19], v[158:161], v[182:185], v[16:19]
	v_mfma_f32_16x16x32_bf16 v[4:7], v[142:145], v[190:193], v[4:7]
	v_mfma_f32_16x16x32_bf16 v[0:3], v[158:161], v[190:193], v[0:3]
	s_barrier
	s_add_i32 s30, 0, 0x18000
	s_add_i32 s31, 0, 0x1c000
	v_add_u32_e32 v126, s30, v232
	v_add_u32_e32 v158, s31, v232
	ds_read_b128 v[98:101], v126
	ds_read_b128 v[106:109], v126 offset:1024
	ds_read_b128 v[118:121], v126 offset:2048
	ds_read_b128 v[126:129], v126 offset:3072
	ds_read_b128 v[138:141], v158
	ds_read_b128 v[142:145], v158 offset:1024
	ds_read_b128 v[150:153], v158 offset:2048
	ds_read_b128 v[158:161], v158 offset:3072
	s_add_u32 s0, s0, s22
	s_addc_u32 s1, s1, 0
	s_mov_b32 m0, s14
	v_lshl_add_u64 v[246:247], s[0:1], 0, v[206:207]
	ds_read_b128 v[162:165], v234 offset:32768
	ds_read_b128 v[166:169], v234 offset:33792
	ds_read_b128 v[170:173], v234 offset:34816
	ds_read_b128 v[174:177], v234 offset:35840
	ds_read_b128 v[178:181], v234 offset:36864
	ds_read_b128 v[182:185], v234 offset:37888
	ds_read_b128 v[186:189], v234 offset:38912
	ds_read_b128 v[190:193], v234 offset:39936
	global_load_lds_dwordx4 v[246:247], off
	v_lshl_add_u64 v[246:247], s[0:1], 0, v[204:205]
	s_mov_b32 m0, s15
	s_nop 0
	global_load_lds_dwordx4 v[246:247], off
	s_waitcnt vmcnt(8)
	s_waitcnt lgkmcnt(0)
	s_barrier
; #define PG8_STAGE(bufoff, gbase, voff) do { _Pragma("unroll") for (int _i = 0; _i < 2; ++_i) \
;         __builtin_amdgcn_global_load_lds((const unsigned*)((const char*)(gbase) + (voff)[_i]), (PG8_LAS unsigned*)(lds + (bufoff) + ldsw + _i * 8192), 16, 0, 0); } while (0)
; #define PG8_LDA(dst, b, h) do { _Pragma("unroll") for (int m = 0; m < 4; ++m) _Pragma("unroll") for (int k = 0; k < 2; ++k) dst[m][k] = *(const PG8_LAS bf16x8*)(lds + PG8_SA(b, h) + aoff + m * 2048 + k * 1024); } while (0)
; #define PG8_MMA(ai, bj, At, Bt) do { __builtin_amdgcn_s_setprio(1); _Pragma("unroll") for (int m = 0; m < 4; ++m) _Pragma("unroll") for (int n = 0; n < 2; ++n) _Pragma("unroll") for (int k = 0; k < 2; ++k) \
;         acc[ai][bj][m][n] = __builtin_amdgcn_mfma_f32_16x16x32_bf16(Bt[n][k], At[m][k], acc[ai][bj][m][n], 0, 0, 0); __builtin_amdgcn_s_setprio(0); } while (0)
; #define PG8_WAIT_V(n) asm volatile("s_waitcnt vmcnt(" #n ")" ::: "memory")
; #define PG8_WAIT_L(n) asm volatile("s_waitcnt lgkmcnt(" #n ")" ::: "memory")
; #define PG8_BAR __builtin_amdgcn_s_barrier()
; #define PG8_SCHED __builtin_amdgcn_sched_barrier(0)
; template <class Epi, class Sched, bool ALIGN_EPI = false, bool SP2 = false>
; __device__ __forceinline__ void gemm_phase(PG8_LAS unsigned char* lds, const Gemm g, const Sched& S, const Epi& E) {
;     ...
;             PG8_WAIT_V(8); PG8_WAIT_L(0); PG8_BAR; PG8_MMA(0, 0, At, B0); PG8_MMA(0, 1, At, B1); PG8_BAR; PG8_SCHED;
;             PG8_LDA(At, 1, 1); PG8_STAGE(PG8_SB(1, 0), b3, voffB); PG8_STAGE(PG8_SB(1, 1), b3 + hstep, voffB); PG8_STAGE(PG8_SA(1, 0), a3, voffA);
;             PG8_WAIT_V(8); PG8_WAIT_L(0); PG8_BAR; PG8_MMA(1, 0, At, B0); PG8_MMA(1, 1, At, B1); PG8_BAR; PG8_SCHED;
	v_mfma_f32_16x16x32_bf16 v[154:157], v[98:101], v[162:165], v[154:157]
	v_mfma_f32_16x16x32_bf16 v[146:149], v[118:121], v[162:165], v[146:149]
	v_mfma_f32_16x16x32_bf16 v[122:125], v[98:101], v[170:173], v[122:125]
	v_mfma_f32_16x16x32_bf16 v[114:117], v[118:121], v[170:173], v[114:117]
	v_mfma_f32_16x16x32_bf16 v[92:95], v[98:101], v[178:181], v[92:95]
	v_mfma_f32_16x16x32_bf16 v[88:91], v[118:121], v[178:181], v[88:91]
	v_mfma_f32_16x16x32_bf16 v[76:79], v[98:101], v[186:189], v[76:79]
	v_mfma_f32_16x16x32_bf16 v[72:75], v[118:121], v[186:189], v[72:75]
	v_mfma_f32_16x16x32_bf16 v[154:157], v[106:109], v[166:169], v[154:157]
	v_mfma_f32_16x16x32_bf16 v[146:149], v[126:129], v[166:169], v[146:149]
	v_mfma_f32_16x16x32_bf16 v[122:125], v[106:109], v[174:177], v[122:125]
	v_mfma_f32_16x16x32_bf16 v[114:117], v[126:129], v[174:177], v[114:117]
	v_mfma_f32_16x16x32_bf16 v[92:95], v[106:109], v[182:185], v[92:95]
	v_mfma_f32_16x16x32_bf16 v[88:91], v[126:129], v[182:185], v[88:91]
	v_mfma_f32_16x16x32_bf16 v[76:79], v[106:109], v[190:193], v[76:79]
	v_mfma_f32_16x16x32_bf16 v[72:75], v[126:129], v[190:193], v[72:75]
	v_mfma_f32_16x16x32_bf16 v[134:137], v[138:141], v[162:165], v[134:137]
	v_mfma_f32_16x16x32_bf16 v[130:133], v[150:153], v[162:165], v[130:133]
	v_mfma_f32_16x16x32_bf16 v[110:113], v[138:141], v[170:173], v[110:113]
	v_mfma_f32_16x16x32_bf16 v[102:105], v[150:153], v[170:173], v[102:105]
	v_mfma_f32_16x16x32_bf16 v[84:87], v[138:141], v[178:181], v[84:87]
	v_mfma_f32_16x16x32_bf16 v[80:83], v[150:153], v[178:181], v[80:83]
	v_mfma_f32_16x16x32_bf16 v[68:71], v[138:141], v[186:189], v[68:71]
	v_mfma_f32_16x16x32_bf16 v[64:67], v[150:153], v[186:189], v[64:67]
	v_mfma_f32_16x16x32_bf16 v[134:137], v[142:145], v[166:169], v[134:137]
	v_mfma_f32_16x16x32_bf16 v[130:133], v[158:161], v[166:169], v[130:133]
	v_mfma_f32_16x16x32_bf16 v[110:113], v[142:145], v[174:177], v[110:113]
	v_mfma_f32_16x16x32_bf16 v[102:105], v[158:161], v[174:177], v[102:105]
	v_mfma_f32_16x16x32_bf16 v[84:87], v[142:145], v[182:185], v[84:87]
	v_mfma_f32_16x16x32_bf16 v[80:83], v[158:161], v[182:185], v[80:83]
	v_mfma_f32_16x16x32_bf16 v[68:71], v[142:145], v[190:193], v[68:71]
	v_mfma_f32_16x16x32_bf16 v[64:67], v[158:161], v[190:193], v[64:67]
	s_barrier
	s_add_i32 s0, s30, s2
	v_lshl_add_u64 v[212:213], v[212:213], 0, s[20:21]
	s_mov_b32 m0, s0
	ds_read_b128 v[162:165], v234 offset:49152
	ds_read_b128 v[166:169], v234 offset:50176
	ds_read_b128 v[170:173], v234 offset:51200
	ds_read_b128 v[174:177], v234 offset:52224
	ds_read_b128 v[178:181], v234 offset:53248
	ds_read_b128 v[182:185], v234 offset:54272
	ds_read_b128 v[186:189], v234 offset:55296
	ds_read_b128 v[190:193], v234 offset:56320
	global_load_lds_dwordx4 v[212:213], off
	v_lshl_add_u64 v[212:213], v[214:215], 0, s[20:21]
	s_add_i32 m0, s0, 0x2000
	s_add_i32 s0, s31, s2
	global_load_lds_dwordx4 v[212:213], off
	v_lshl_add_u64 v[212:213], v[228:229], 0, s[20:21]
	s_mov_b32 m0, s0
	s_nop 0
	global_load_lds_dwordx4 v[212:213], off
	v_lshl_add_u64 v[212:213], v[236:237], 0, s[20:21]
	s_add_i32 m0, s0, 0x2000
	s_nop 0
	global_load_lds_dwordx4 v[212:213], off
	v_lshl_add_u64 v[212:213], v[242:243], 0, s[20:21]
	s_mov_b32 m0, s19
	s_nop 0
	global_load_lds_dwordx4 v[212:213], off
	v_lshl_add_u64 v[212:213], v[244:245], 0, s[20:21]
	s_mov_b32 m0, s46
	s_nop 0
	global_load_lds_dwordx4 v[212:213], off
	s_waitcnt vmcnt(8)
	s_waitcnt lgkmcnt(0)
	s_barrier
	v_mfma_f32_16x16x32_bf16 v[60:63], v[98:101], v[162:165], v[60:63]
	v_mfma_f32_16x16x32_bf16 v[56:59], v[118:121], v[162:165], v[56:59]
	v_mfma_f32_16x16x32_bf16 v[44:47], v[98:101], v[170:173], v[44:47]
	v_mfma_f32_16x16x32_bf16 v[40:43], v[118:121], v[170:173], v[40:43]
	v_mfma_f32_16x16x32_bf16 v[28:31], v[98:101], v[178:181], v[28:31]
	v_mfma_f32_16x16x32_bf16 v[24:27], v[118:121], v[178:181], v[24:27]
	v_mfma_f32_16x16x32_bf16 v[12:15], v[98:101], v[186:189], v[12:15]
	v_mfma_f32_16x16x32_bf16 v[8:11], v[118:121], v[186:189], v[8:11]
	v_mfma_f32_16x16x32_bf16 v[60:63], v[106:109], v[166:169], v[60:63]
	v_mfma_f32_16x16x32_bf16 v[56:59], v[126:129], v[166:169], v[56:59]
	v_mfma_f32_16x16x32_bf16 v[44:47], v[106:109], v[174:177], v[44:47]
	v_mfma_f32_16x16x32_bf16 v[40:43], v[126:129], v[174:177], v[40:43]
	v_mfma_f32_16x16x32_bf16 v[28:31], v[106:109], v[182:185], v[28:31]
	v_mfma_f32_16x16x32_bf16 v[24:27], v[126:129], v[182:185], v[24:27]
	v_mfma_f32_16x16x32_bf16 v[12:15], v[106:109], v[190:193], v[12:15]
	v_mfma_f32_16x16x32_bf16 v[8:11], v[126:129], v[190:193], v[8:11]
	v_mfma_f32_16x16x32_bf16 v[52:55], v[138:141], v[162:165], v[52:55]
	v_mfma_f32_16x16x32_bf16 v[48:51], v[150:153], v[162:165], v[48:51]
	v_mfma_f32_16x16x32_bf16 v[36:39], v[138:141], v[170:173], v[36:39]
	v_mfma_f32_16x16x32_bf16 v[32:35], v[150:153], v[170:173], v[32:35]
	v_mfma_f32_16x16x32_bf16 v[20:23], v[138:141], v[178:181], v[20:23]
	v_mfma_f32_16x16x32_bf16 v[16:19], v[150:153], v[178:181], v[16:19]
	v_mfma_f32_16x16x32_bf16 v[4:7], v[138:141], v[186:189], v[4:7]
	v_mfma_f32_16x16x32_bf16 v[0:3], v[150:153], v[186:189], v[0:3]
	v_mfma_f32_16x16x32_bf16 v[52:55], v[142:145], v[166:169], v[52:55]
	v_mfma_f32_16x16x32_bf16 v[48:51], v[158:161], v[166:169], v[48:51]
	v_mfma_f32_16x16x32_bf16 v[36:39], v[142:145], v[174:177], v[36:39]
	v_mfma_f32_16x16x32_bf16 v[32:35], v[158:161], v[174:177], v[32:35]
	v_mfma_f32_16x16x32_bf16 v[20:23], v[142:145], v[182:185], v[20:23]
	v_mfma_f32_16x16x32_bf16 v[16:19], v[158:161], v[182:185], v[16:19]
	v_mfma_f32_16x16x32_bf16 v[4:7], v[142:145], v[190:193], v[4:7]
	v_mfma_f32_16x16x32_bf16 v[0:3], v[158:161], v[190:193], v[0:3]
	s_barrier
	s_add_u32 s17, s17, 0x100
	s_addc_u32 s23, s23, 0
	s_add_u32 s66, s66, 0x100
	s_addc_u32 s67, s67, 0
	s_cmp_ge_u32 s28, s49
	s_mov_b32 s0, s28
	s_cbranch_scc0 .LBB0_447
	s_and_b64 vcc, exec, s[62:63]
	s_cbranch_vccz .LBB0_450
	s_barrier

; #define PG8_WAIT_V(n) asm volatile("s_waitcnt vmcnt(" #n ")" ::: "memory")
; #define PG8_BAR __builtin_amdgcn_s_barrier()
; template <class Epi, class Sched, bool ALIGN_EPI = false, bool SP2 = false>
; __device__ __forceinline__ void gemm_phase(PG8_LAS unsigned char* lds, const Gemm g, const Sched& S, const Epi& E) {
;     ...
;     PG8_WAIT_V(0);
;     if constexpr (!ALIGN_EPI) { if (wr == 0) PG8_BAR; }
;     PG8_BAR;
.LBB0_469:
	s_setprio 0
	s_waitcnt vmcnt(0)
	v_readlane_b32 s63, v254, 44
	v_readlane_b32 s33, v254, 45
	v_readlane_b32 s40, v254, 46
	v_readlane_b32 s41, v254, 47
	s_barrier

; #define PG8_WAIT_V(n) asm volatile("s_waitcnt vmcnt(" #n ")" ::: "memory")
; #define PG8_BAR __builtin_amdgcn_s_barrier()
; template <class Epi, class Sched, bool ALIGN_EPI = false, bool SP2 = false>
; __device__ __forceinline__ void gemm_phase(PG8_LAS unsigned char* lds, const Gemm g, const Sched& S, const Epi& E) {
;     ...
;     PG8_WAIT_V(0);
;     if constexpr (!ALIGN_EPI) { if (wr == 0) PG8_BAR; }
;     PG8_BAR;
.LBB0_473:
	s_setprio 0
	s_waitcnt vmcnt(0)
	v_readlane_b32 s44, v254, 48
	s_mov_b32 s93, s62
	v_readlane_b32 s33, v254, 45
	v_readlane_b32 s40, v254, 46
	v_readlane_b32 s41, v254, 47
	v_readlane_b32 s45, v254, 49
	v_readlane_b32 s77, v254, 56
	s_barrier

; #define PG8_STAGE(bufoff, gbase, voff) do { _Pragma("unroll") for (int _i = 0; _i < 2; ++_i) \
;         __builtin_amdgcn_global_load_lds((const unsigned*)((const char*)(gbase) + (voff)[_i]), (PG8_LAS unsigned*)(lds + (bufoff) + ldsw + _i * 8192), 16, 0, 0); } while (0)
; #define PG8_LDA(dst, b, h) do { _Pragma("unroll") for (int m = 0; m < 4; ++m) _Pragma("unroll") for (int k = 0; k < 2; ++k) dst[m][k] = *(const PG8_LAS bf16x8*)(lds + PG8_SA(b, h) + aoff + m * 2048 + k * 1024); } while (0)
; #define PG8_LDB(dst, b, h) do { _Pragma("unroll") for (int n = 0; n < 2; ++n) _Pragma("unroll") for (int k = 0; k < 2; ++k) dst[n][k] = *(const PG8_LAS bf16x8*)(lds + PG8_SB(b, h) + boff + n * 2048 + k * 1024); } while (0)
; #define PG8_MMA(ai, bj, At, Bt) do { __builtin_amdgcn_s_setprio(1); _Pragma("unroll") for (int m = 0; m < 4; ++m) _Pragma("unroll") for (int n = 0; n < 2; ++n) _Pragma("unroll") for (int k = 0; k < 2; ++k) \
;         acc[ai][bj][m][n] = __builtin_amdgcn_mfma_f32_16x16x32_bf16(Bt[n][k], At[m][k], acc[ai][bj][m][n], 0, 0, 0); __builtin_amdgcn_s_setprio(0); } while (0)
; #define PG8_WAIT_V(n) asm volatile("s_waitcnt vmcnt(" #n ")" ::: "memory")
; #define PG8_WAIT_L(n) asm volatile("s_waitcnt lgkmcnt(" #n ")" ::: "memory")
; template <class Epi, class Sched, bool ALIGN_EPI = false, bool SP2 = false>
; __device__ __forceinline__ void gemm_phase(PG8_LAS unsigned char* lds, const Gemm g, const Sched& S, const Epi& E) {
;     ...
;             const bool last = (t == nt - 2);
;             const char* a1 = cA + (size_t)(t + 1) * kstep;
;             const char* a2 = last ? nA : cA + (size_t)(t + 2) * kstep; const char* b2 = last ? nB : cB + (size_t)(t + 2) * kstep;
;             const char* a3 = a2 + kstep; const char* b3 = b2 + kstep;
;             if (last && has_next) S.a_ready(nxt);
;             if constexpr (SP2) {
;             PG8_LDB(B0, 0, 0); PG8_LDB(B1, 0, 1); PG8_SCHED; PG8_LDA(At, 0, 0); PG8_STAGE(PG8_SA(1, 1), a1 + hstep, voffA);
;             PG8_WAIT_V(8); PG8_WAIT_L(0); PG8_BAR; PG8_MMA(0, 0, At, B0); PG8_MMA(0, 1, At, B1); PG8_BAR; PG8_SCHED;
;     ...
;         for (int a = 0; a < 2; ++a)
; #pragma unroll
;             for (int b = 0; b < 2; ++b)
; #pragma unroll
;                 for (int m = 0; m < 4; ++m)
; #pragma unroll
;                     for (int n = 0; n < 2; ++n) acc[a][b][m][n] = (f32x4){0.f, 0.f, 0.f, 0.f};
.LBB0_509:
	s_add_u32 s45, s94, 0x100
	s_addc_u32 s94, s95, 0
	s_add_u32 s40, s96, 0x80
	v_mov_b32_e32 v0, 0
	s_addc_u32 s41, s97, 0
	s_mov_b32 s0, 0
	v_mov_b32_e32 v1, v0
	v_mov_b32_e32 v2, v0
	v_mov_b32_e32 v3, v0
	v_mov_b32_e32 v4, v0
	v_mov_b32_e32 v5, v0
	v_mov_b32_e32 v6, v0
	v_mov_b32_e32 v7, v0
	v_mov_b32_e32 v12, v0
	v_mov_b32_e32 v13, v0
	v_mov_b32_e32 v14, v0
	v_mov_b32_e32 v15, v0
	v_mov_b32_e32 v20, v0
	v_mov_b32_e32 v21, v0
	v_mov_b32_e32 v22, v0
	v_mov_b32_e32 v23, v0
	v_mov_b32_e32 v28, v0
	v_mov_b32_e32 v29, v0
	v_mov_b32_e32 v30, v0
	v_mov_b32_e32 v31, v0
	v_mov_b32_e32 v36, v0
	v_mov_b32_e32 v37, v0
	v_mov_b32_e32 v38, v0
	v_mov_b32_e32 v39, v0
	v_mov_b32_e32 v44, v0
	v_mov_b32_e32 v45, v0
	v_mov_b32_e32 v46, v0
	v_mov_b32_e32 v47, v0
	v_mov_b32_e32 v52, v0
	v_mov_b32_e32 v53, v0
	v_mov_b32_e32 v54, v0
	v_mov_b32_e32 v55, v0
	v_mov_b32_e32 v8, v0
	v_mov_b32_e32 v9, v0
	v_mov_b32_e32 v10, v0
	v_mov_b32_e32 v11, v0
	v_mov_b32_e32 v16, v0
	v_mov_b32_e32 v17, v0
	v_mov_b32_e32 v18, v0
	v_mov_b32_e32 v19, v0
	v_mov_b32_e32 v24, v0
	v_mov_b32_e32 v25, v0
	v_mov_b32_e32 v26, v0
	v_mov_b32_e32 v27, v0
	v_mov_b32_e32 v32, v0
	v_mov_b32_e32 v33, v0
	v_mov_b32_e32 v34, v0
	v_mov_b32_e32 v35, v0
	v_mov_b32_e32 v40, v0
	v_mov_b32_e32 v41, v0
	v_mov_b32_e32 v42, v0
	v_mov_b32_e32 v43, v0
	v_mov_b32_e32 v48, v0
	v_mov_b32_e32 v49, v0
	v_mov_b32_e32 v50, v0
	v_mov_b32_e32 v51, v0
	v_mov_b32_e32 v56, v0
	v_mov_b32_e32 v57, v0
	v_mov_b32_e32 v58, v0
	v_mov_b32_e32 v59, v0
	v_mov_b32_e32 v60, v0
	v_mov_b32_e32 v61, v0
	v_mov_b32_e32 v62, v0
	v_mov_b32_e32 v63, v0
	v_mov_b32_e32 v64, v0
	v_mov_b32_e32 v65, v0
	v_mov_b32_e32 v66, v0
	v_mov_b32_e32 v67, v0
	v_mov_b32_e32 v68, v0
	v_mov_b32_e32 v69, v0
	v_mov_b32_e32 v70, v0
	v_mov_b32_e32 v71, v0
	v_mov_b32_e32 v76, v0
	v_mov_b32_e32 v77, v0
	v_mov_b32_e32 v78, v0
	v_mov_b32_e32 v79, v0
	v_mov_b32_e32 v84, v0
	v_mov_b32_e32 v85, v0
	v_mov_b32_e32 v86, v0
	v_mov_b32_e32 v87, v0
	v_mov_b32_e32 v92, v0
	v_mov_b32_e32 v93, v0
	v_mov_b32_e32 v94, v0
	v_mov_b32_e32 v95, v0
	v_mov_b32_e32 v102, v0
	v_mov_b32_e32 v103, v0
	v_mov_b32_e32 v104, v0
	v_mov_b32_e32 v105, v0
	v_mov_b32_e32 v110, v0
	v_mov_b32_e32 v111, v0
	v_mov_b32_e32 v112, v0
	v_mov_b32_e32 v113, v0
	v_mov_b32_e32 v118, v0
	v_mov_b32_e32 v119, v0
	v_mov_b32_e32 v120, v0
	v_mov_b32_e32 v121, v0
	v_mov_b32_e32 v72, v0
	v_mov_b32_e32 v73, v0
	v_mov_b32_e32 v74, v0
	v_mov_b32_e32 v75, v0
	v_mov_b32_e32 v80, v0
	v_mov_b32_e32 v81, v0
	v_mov_b32_e32 v82, v0
	v_mov_b32_e32 v83, v0
	v_mov_b32_e32 v88, v0
	v_mov_b32_e32 v89, v0
	v_mov_b32_e32 v90, v0
	v_mov_b32_e32 v91, v0
	v_mov_b32_e32 v98, v0
	v_mov_b32_e32 v99, v0
	v_mov_b32_e32 v100, v0
	v_mov_b32_e32 v101, v0
	v_mov_b32_e32 v106, v0
	v_mov_b32_e32 v107, v0
	v_mov_b32_e32 v108, v0
	v_mov_b32_e32 v109, v0
	v_mov_b32_e32 v114, v0
	v_mov_b32_e32 v115, v0
	v_mov_b32_e32 v116, v0
	v_mov_b32_e32 v117, v0
	v_mov_b32_e32 v122, v0
	v_mov_b32_e32 v123, v0
	v_mov_b32_e32 v124, v0
	v_mov_b32_e32 v125, v0
	v_mov_b32_e32 v126, v0
	v_mov_b32_e32 v127, v0
	v_mov_b32_e32 v128, v0
	v_mov_b32_e32 v129, v0
	s_cmp_lg_u64 s[82:83], 0
	s_cbranch_scc1 .Lgp_c
	s_setprio 1
.Lgp_c:
.LBB0_510:
	s_add_i32 s95, s0, 2
	s_add_u32 s96, s40, 0x80
	s_addc_u32 s1, s41, 0
	s_add_i32 vcc_lo, 0, 0x10000
	s_cmp_eq_u32 s7, s0
	s_cselect_b32 s1, s89, s1
	s_cselect_b32 s0, s88, s96
	s_cselect_b32 s97, s87, s94
	s_cselect_b32 s96, s86, s45
	s_add_i32 vcc_hi, 0, 0x14000
	v_add_u32_e32 v142, vcc_lo, v193
	v_add_u32_e32 v158, vcc_hi, v193
	ds_read_b128 v[130:133], v142
	ds_read_b128 v[134:137], v142 offset:1024
	ds_read_b128 v[138:141], v142 offset:2048
	ds_read_b128 v[142:145], v142 offset:3072
	ds_read_b128 v[146:149], v158
	ds_read_b128 v[150:153], v158 offset:1024
	ds_read_b128 v[154:157], v158 offset:2048
	ds_read_b128 v[158:161], v158 offset:3072
	v_lshl_add_u64 v[202:203], s[40:41], 0, v[188:189]
	s_add_i32 m0, s90, 0xc000
	ds_read_b128 v[162:165], v207
	ds_read_b128 v[166:169], v207 offset:1024
	ds_read_b128 v[170:173], v207 offset:2048
	ds_read_b128 v[174:177], v207 offset:3072
	ds_read_b128 v[208:211], v207 offset:4096
	ds_read_b128 v[212:215], v207 offset:5120
	ds_read_b128 v[232:235], v207 offset:6144
	ds_read_b128 v[242:245], v207 offset:7168
	global_load_lds_dwordx4 v[202:203], off
	v_lshl_add_u64 v[202:203], s[40:41], 0, v[186:187]
	s_add_i32 m0, s90, 0xe000
	s_nop 0
	global_load_lds_dwordx4 v[202:203], off
	s_waitcnt vmcnt(8)
	s_waitcnt lgkmcnt(0)
	s_barrier
	v_mfma_f32_16x16x32_bf16 v[126:129], v[130:133], v[162:165], v[126:129]
	v_mfma_f32_16x16x32_bf16 v[122:125], v[138:141], v[162:165], v[122:125]
	v_mfma_f32_16x16x32_bf16 v[114:117], v[130:133], v[170:173], v[114:117]
	v_mfma_f32_16x16x32_bf16 v[106:109], v[138:141], v[170:173], v[106:109]
	v_mfma_f32_16x16x32_bf16 v[98:101], v[130:133], v[208:211], v[98:101]
	v_mfma_f32_16x16x32_bf16 v[88:91], v[138:141], v[208:211], v[88:91]
	v_mfma_f32_16x16x32_bf16 v[80:83], v[130:133], v[232:235], v[80:83]
	v_mfma_f32_16x16x32_bf16 v[72:75], v[138:141], v[232:235], v[72:75]
	v_mfma_f32_16x16x32_bf16 v[126:129], v[134:137], v[166:169], v[126:129]
	v_mfma_f32_16x16x32_bf16 v[122:125], v[142:145], v[166:169], v[122:125]
	v_mfma_f32_16x16x32_bf16 v[114:117], v[134:137], v[174:177], v[114:117]
	v_mfma_f32_16x16x32_bf16 v[106:109], v[142:145], v[174:177], v[106:109]
	v_mfma_f32_16x16x32_bf16 v[98:101], v[134:137], v[212:215], v[98:101]
	v_mfma_f32_16x16x32_bf16 v[88:91], v[142:145], v[212:215], v[88:91]
	v_mfma_f32_16x16x32_bf16 v[80:83], v[134:137], v[242:245], v[80:83]
	v_mfma_f32_16x16x32_bf16 v[72:75], v[142:145], v[242:245], v[72:75]
	v_mfma_f32_16x16x32_bf16 v[118:121], v[146:149], v[162:165], v[118:121]
	v_mfma_f32_16x16x32_bf16 v[110:113], v[154:157], v[162:165], v[110:113]
	v_mfma_f32_16x16x32_bf16 v[102:105], v[146:149], v[170:173], v[102:105]
	v_mfma_f32_16x16x32_bf16 v[92:95], v[154:157], v[170:173], v[92:95]
	v_mfma_f32_16x16x32_bf16 v[84:87], v[146:149], v[208:211], v[84:87]
	v_mfma_f32_16x16x32_bf16 v[76:79], v[154:157], v[208:211], v[76:79]
	v_mfma_f32_16x16x32_bf16 v[68:71], v[146:149], v[232:235], v[68:71]
	v_mfma_f32_16x16x32_bf16 v[64:67], v[154:157], v[232:235], v[64:67]
	v_mfma_f32_16x16x32_bf16 v[118:121], v[150:153], v[166:169], v[118:121]
	v_mfma_f32_16x16x32_bf16 v[110:113], v[158:161], v[166:169], v[110:113]
	v_mfma_f32_16x16x32_bf16 v[102:105], v[150:153], v[174:177], v[102:105]
	v_mfma_f32_16x16x32_bf16 v[92:95], v[158:161], v[174:177], v[92:95]
	v_mfma_f32_16x16x32_bf16 v[84:87], v[150:153], v[212:215], v[84:87]
	v_mfma_f32_16x16x32_bf16 v[76:79], v[158:161], v[212:215], v[76:79]
	v_mfma_f32_16x16x32_bf16 v[68:71], v[150:153], v[242:245], v[68:71]
	v_mfma_f32_16x16x32_bf16 v[64:67], v[158:161], v[242:245], v[64:67]
	s_barrier
; #define PG8_STAGE(bufoff, gbase, voff) do { _Pragma("unroll") for (int _i = 0; _i < 2; ++_i) \
;         __builtin_amdgcn_global_load_lds((const unsigned*)((const char*)(gbase) + (voff)[_i]), (PG8_LAS unsigned*)(lds + (bufoff) + ldsw + _i * 8192), 16, 0, 0); } while (0)
; #define PG8_LDA(dst, b, h) do { _Pragma("unroll") for (int m = 0; m < 4; ++m) _Pragma("unroll") for (int k = 0; k < 2; ++k) dst[m][k] = *(const PG8_LAS bf16x8*)(lds + PG8_SA(b, h) + aoff + m * 2048 + k * 1024); } while (0)
; #define PG8_LDB(dst, b, h) do { _Pragma("unroll") for (int n = 0; n < 2; ++n) _Pragma("unroll") for (int k = 0; k < 2; ++k) dst[n][k] = *(const PG8_LAS bf16x8*)(lds + PG8_SB(b, h) + boff + n * 2048 + k * 1024); } while (0)
; #define PG8_MMA(ai, bj, At, Bt) do { __builtin_amdgcn_s_setprio(1); _Pragma("unroll") for (int m = 0; m < 4; ++m) _Pragma("unroll") for (int n = 0; n < 2; ++n) _Pragma("unroll") for (int k = 0; k < 2; ++k) \
;         acc[ai][bj][m][n] = __builtin_amdgcn_mfma_f32_16x16x32_bf16(Bt[n][k], At[m][k], acc[ai][bj][m][n], 0, 0, 0); __builtin_amdgcn_s_setprio(0); } while (0)
; #define PG8_WAIT_V(n) asm volatile("s_waitcnt vmcnt(" #n ")" ::: "memory")
; #define PG8_WAIT_L(n) asm volatile("s_waitcnt lgkmcnt(" #n ")" ::: "memory")
; #define PG8_BAR __builtin_amdgcn_s_barrier()
; #define PG8_SCHED __builtin_amdgcn_sched_barrier(0)
; template <class Epi, class Sched, bool ALIGN_EPI = false, bool SP2 = false>
; __device__ __forceinline__ void gemm_phase(PG8_LAS unsigned char* lds, const Gemm g, const Sched& S, const Epi& E) {
;     ...
;             PG8_LDA(At, 0, 1); PG8_STAGE(PG8_SB(0, 0), b2, voffB); PG8_STAGE(PG8_SB(0, 1), b2 + hstep, voffB); PG8_STAGE(PG8_SA(0, 0), a2, voffA);
;             PG8_WAIT_V(8); PG8_WAIT_L(0); PG8_BAR; PG8_MMA(1, 0, At, B0); PG8_MMA(1, 1, At, B1); PG8_BAR; PG8_SCHED;
;             PG8_LDB(B0, 1, 0); PG8_LDB(B1, 1, 1); PG8_SCHED; PG8_LDA(At, 1, 0); PG8_STAGE(PG8_SA(0, 1), a2 + hstep, voffA);
;             PG8_WAIT_V(8); PG8_WAIT_L(0); PG8_BAR; PG8_MMA(0, 0, At, B0); PG8_MMA(0, 1, At, B1); PG8_BAR; PG8_SCHED;
	s_add_i32 vcc_lo, vcc_lo, s4
	v_lshl_add_u64 v[202:203], s[96:97], 0, v[96:97]
	s_mov_b32 m0, vcc_lo
	ds_read_b128 v[162:165], v207 offset:16384
	ds_read_b128 v[166:169], v207 offset:17408
	ds_read_b128 v[170:173], v207 offset:18432
	ds_read_b128 v[174:177], v207 offset:19456
	ds_read_b128 v[208:211], v207 offset:20480
	ds_read_b128 v[212:215], v207 offset:21504
	ds_read_b128 v[232:235], v207 offset:22528
	ds_read_b128 v[242:245], v207 offset:23552
	global_load_lds_dwordx4 v[202:203], off
	s_add_i32 m0, vcc_lo, 0x2000
	v_lshl_add_u64 v[228:229], s[96:97], 0, v[178:179]
	s_add_u32 s96, s96, s28
	s_addc_u32 s97, s97, 0
	s_add_i32 vcc_lo, vcc_hi, s4
	global_load_lds_dwordx4 v[228:229], off
	v_lshl_add_u64 v[230:231], s[96:97], 0, v[96:97]
	s_mov_b32 m0, vcc_lo
	v_lshl_add_u64 v[246:247], s[96:97], 0, v[178:179]
	global_load_lds_dwordx4 v[230:231], off
	s_add_i32 m0, vcc_lo, 0x2000
	v_lshl_add_u64 v[248:249], s[0:1], 0, v[182:183]
	global_load_lds_dwordx4 v[246:247], off
	s_mov_b32 m0, s90
	v_lshl_add_u64 v[236:237], s[0:1], 0, v[180:181]
	global_load_lds_dwordx4 v[248:249], off
	s_mov_b32 m0, s8
	s_nop 0
	global_load_lds_dwordx4 v[236:237], off
	s_waitcnt vmcnt(8)
	s_waitcnt lgkmcnt(0)
	s_barrier
	v_mfma_f32_16x16x32_bf16 v[60:63], v[130:133], v[162:165], v[60:63]
	v_mfma_f32_16x16x32_bf16 v[56:59], v[138:141], v[162:165], v[56:59]
	v_mfma_f32_16x16x32_bf16 v[48:51], v[130:133], v[170:173], v[48:51]
	v_mfma_f32_16x16x32_bf16 v[40:43], v[138:141], v[170:173], v[40:43]
	v_mfma_f32_16x16x32_bf16 v[32:35], v[130:133], v[208:211], v[32:35]
	v_mfma_f32_16x16x32_bf16 v[24:27], v[138:141], v[208:211], v[24:27]
	v_mfma_f32_16x16x32_bf16 v[16:19], v[130:133], v[232:235], v[16:19]
	v_mfma_f32_16x16x32_bf16 v[8:11], v[138:141], v[232:235], v[8:11]
	v_mfma_f32_16x16x32_bf16 v[60:63], v[134:137], v[166:169], v[60:63]
	v_mfma_f32_16x16x32_bf16 v[56:59], v[142:145], v[166:169], v[56:59]
	v_mfma_f32_16x16x32_bf16 v[48:51], v[134:137], v[174:177], v[48:51]
	v_mfma_f32_16x16x32_bf16 v[40:43], v[142:145], v[174:177], v[40:43]
	v_mfma_f32_16x16x32_bf16 v[32:35], v[134:137], v[212:215], v[32:35]
	v_mfma_f32_16x16x32_bf16 v[24:27], v[142:145], v[212:215], v[24:27]
	v_mfma_f32_16x16x32_bf16 v[16:19], v[134:137], v[242:245], v[16:19]
	v_mfma_f32_16x16x32_bf16 v[8:11], v[142:145], v[242:245], v[8:11]
	v_mfma_f32_16x16x32_bf16 v[52:55], v[146:149], v[162:165], v[52:55]
	v_mfma_f32_16x16x32_bf16 v[44:47], v[154:157], v[162:165], v[44:47]
	v_mfma_f32_16x16x32_bf16 v[36:39], v[146:149], v[170:173], v[36:39]
	v_mfma_f32_16x16x32_bf16 v[28:31], v[154:157], v[170:173], v[28:31]
	v_mfma_f32_16x16x32_bf16 v[20:23], v[146:149], v[208:211], v[20:23]
	v_mfma_f32_16x16x32_bf16 v[12:15], v[154:157], v[208:211], v[12:15]
	v_mfma_f32_16x16x32_bf16 v[4:7], v[146:149], v[232:235], v[4:7]
	v_mfma_f32_16x16x32_bf16 v[0:3], v[154:157], v[232:235], v[0:3]
	v_mfma_f32_16x16x32_bf16 v[52:55], v[150:153], v[166:169], v[52:55]
	v_mfma_f32_16x16x32_bf16 v[44:47], v[158:161], v[166:169], v[44:47]
	v_mfma_f32_16x16x32_bf16 v[36:39], v[150:153], v[174:177], v[36:39]
	v_mfma_f32_16x16x32_bf16 v[28:31], v[158:161], v[174:177], v[28:31]
	v_mfma_f32_16x16x32_bf16 v[20:23], v[150:153], v[212:215], v[20:23]
	v_mfma_f32_16x16x32_bf16 v[12:15], v[158:161], v[212:215], v[12:15]
	v_mfma_f32_16x16x32_bf16 v[4:7], v[150:153], v[242:245], v[4:7]
	v_mfma_f32_16x16x32_bf16 v[0:3], v[158:161], v[242:245], v[0:3]
	s_barrier
	s_add_i32 s96, 0, 0x18000
	s_add_i32 s97, 0, 0x1c000
	v_add_u32_e32 v142, s96, v193
	v_add_u32_e32 v158, s97, v193
	ds_read_b128 v[130:133], v142
	ds_read_b128 v[134:137], v142 offset:1024
	ds_read_b128 v[138:141], v142 offset:2048
	ds_read_b128 v[142:145], v142 offset:3072
	ds_read_b128 v[146:149], v158
	ds_read_b128 v[150:153], v158 offset:1024
	ds_read_b128 v[154:157], v158 offset:2048
	ds_read_b128 v[158:161], v158 offset:3072
	s_add_u32 s0, s0, s28
	s_addc_u32 s1, s1, 0
	s_mov_b32 m0, s9
	v_lshl_add_u64 v[250:251], s[0:1], 0, v[182:183]
	ds_read_b128 v[162:165], v207 offset:32768
	ds_read_b128 v[166:169], v207 offset:33792
	ds_read_b128 v[170:173], v207 offset:34816
	ds_read_b128 v[174:177], v207 offset:35840
	ds_read_b128 v[208:211], v207 offset:36864
	ds_read_b128 v[212:215], v207 offset:37888
	ds_read_b128 v[232:235], v207 offset:38912
	ds_read_b128 v[242:245], v207 offset:39936
	global_load_lds_dwordx4 v[250:251], off
	v_lshl_add_u64 v[250:251], s[0:1], 0, v[180:181]
	s_mov_b32 m0, s33
	s_nop 0
	global_load_lds_dwordx4 v[250:251], off
	s_waitcnt vmcnt(8)
	s_waitcnt lgkmcnt(0)
	s_barrier
; #define PG8_STAGE(bufoff, gbase, voff) do { _Pragma("unroll") for (int _i = 0; _i < 2; ++_i) \
;         __builtin_amdgcn_global_load_lds((const unsigned*)((const char*)(gbase) + (voff)[_i]), (PG8_LAS unsigned*)(lds + (bufoff) + ldsw + _i * 8192), 16, 0, 0); } while (0)
; #define PG8_LDA(dst, b, h) do { _Pragma("unroll") for (int m = 0; m < 4; ++m) _Pragma("unroll") for (int k = 0; k < 2; ++k) dst[m][k] = *(const PG8_LAS bf16x8*)(lds + PG8_SA(b, h) + aoff + m * 2048 + k * 1024); } while (0)
; #define PG8_MMA(ai, bj, At, Bt) do { __builtin_amdgcn_s_setprio(1); _Pragma("unroll") for (int m = 0; m < 4; ++m) _Pragma("unroll") for (int n = 0; n < 2; ++n) _Pragma("unroll") for (int k = 0; k < 2; ++k) \
;         acc[ai][bj][m][n] = __builtin_amdgcn_mfma_f32_16x16x32_bf16(Bt[n][k], At[m][k], acc[ai][bj][m][n], 0, 0, 0); __builtin_amdgcn_s_setprio(0); } while (0)
; #define PG8_WAIT_V(n) asm volatile("s_waitcnt vmcnt(" #n ")" ::: "memory")
; #define PG8_WAIT_L(n) asm volatile("s_waitcnt lgkmcnt(" #n ")" ::: "memory")
; #define PG8_BAR __builtin_amdgcn_s_barrier()
; #define PG8_SCHED __builtin_amdgcn_sched_barrier(0)
; template <class Epi, class Sched, bool ALIGN_EPI = false, bool SP2 = false>
; __device__ __forceinline__ void gemm_phase(PG8_LAS unsigned char* lds, const Gemm g, const Sched& S, const Epi& E) {
;     ...
;             PG8_WAIT_V(8); PG8_WAIT_L(0); PG8_BAR; PG8_MMA(0, 0, At, B0); PG8_MMA(0, 1, At, B1); PG8_BAR; PG8_SCHED;
;             PG8_LDA(At, 1, 1); PG8_STAGE(PG8_SB(1, 0), b3, voffB); PG8_STAGE(PG8_SB(1, 1), b3 + hstep, voffB); PG8_STAGE(PG8_SA(1, 0), a3, voffA);
;             PG8_WAIT_V(8); PG8_WAIT_L(0); PG8_BAR; PG8_MMA(1, 0, At, B0); PG8_MMA(1, 1, At, B1); PG8_BAR; PG8_SCHED;
;     ...
;         if constexpr (ALIGN_EPI) { if (wr == 0) PG8_BAR; }
	v_mfma_f32_16x16x32_bf16 v[126:129], v[130:133], v[162:165], v[126:129]
	v_mfma_f32_16x16x32_bf16 v[122:125], v[138:141], v[162:165], v[122:125]
	v_mfma_f32_16x16x32_bf16 v[114:117], v[130:133], v[170:173], v[114:117]
	v_mfma_f32_16x16x32_bf16 v[106:109], v[138:141], v[170:173], v[106:109]
	v_mfma_f32_16x16x32_bf16 v[98:101], v[130:133], v[208:211], v[98:101]
	v_mfma_f32_16x16x32_bf16 v[88:91], v[138:141], v[208:211], v[88:91]
	v_mfma_f32_16x16x32_bf16 v[80:83], v[130:133], v[232:235], v[80:83]
	v_mfma_f32_16x16x32_bf16 v[72:75], v[138:141], v[232:235], v[72:75]
	v_mfma_f32_16x16x32_bf16 v[126:129], v[134:137], v[166:169], v[126:129]
	v_mfma_f32_16x16x32_bf16 v[122:125], v[142:145], v[166:169], v[122:125]
	v_mfma_f32_16x16x32_bf16 v[114:117], v[134:137], v[174:177], v[114:117]
	v_mfma_f32_16x16x32_bf16 v[106:109], v[142:145], v[174:177], v[106:109]
	v_mfma_f32_16x16x32_bf16 v[98:101], v[134:137], v[212:215], v[98:101]
	v_mfma_f32_16x16x32_bf16 v[88:91], v[142:145], v[212:215], v[88:91]
	v_mfma_f32_16x16x32_bf16 v[80:83], v[134:137], v[242:245], v[80:83]
	v_mfma_f32_16x16x32_bf16 v[72:75], v[142:145], v[242:245], v[72:75]
	v_mfma_f32_16x16x32_bf16 v[118:121], v[146:149], v[162:165], v[118:121]
	v_mfma_f32_16x16x32_bf16 v[110:113], v[154:157], v[162:165], v[110:113]
	v_mfma_f32_16x16x32_bf16 v[102:105], v[146:149], v[170:173], v[102:105]
	v_mfma_f32_16x16x32_bf16 v[92:95], v[154:157], v[170:173], v[92:95]
	v_mfma_f32_16x16x32_bf16 v[84:87], v[146:149], v[208:211], v[84:87]
	v_mfma_f32_16x16x32_bf16 v[76:79], v[154:157], v[208:211], v[76:79]
	v_mfma_f32_16x16x32_bf16 v[68:71], v[146:149], v[232:235], v[68:71]
	v_mfma_f32_16x16x32_bf16 v[64:67], v[154:157], v[232:235], v[64:67]
	v_mfma_f32_16x16x32_bf16 v[118:121], v[150:153], v[166:169], v[118:121]
	v_mfma_f32_16x16x32_bf16 v[110:113], v[158:161], v[166:169], v[110:113]
	v_mfma_f32_16x16x32_bf16 v[102:105], v[150:153], v[174:177], v[102:105]
	v_mfma_f32_16x16x32_bf16 v[92:95], v[158:161], v[174:177], v[92:95]
	v_mfma_f32_16x16x32_bf16 v[84:87], v[150:153], v[212:215], v[84:87]
	v_mfma_f32_16x16x32_bf16 v[76:79], v[158:161], v[212:215], v[76:79]
	v_mfma_f32_16x16x32_bf16 v[68:71], v[150:153], v[242:245], v[68:71]
	v_mfma_f32_16x16x32_bf16 v[64:67], v[158:161], v[242:245], v[64:67]
	s_barrier
	s_add_i32 s0, s96, s4
	v_lshl_add_u64 v[202:203], v[202:203], 0, s[20:21]
	s_mov_b32 m0, s0
	ds_read_b128 v[162:165], v207 offset:49152
	ds_read_b128 v[166:169], v207 offset:50176
	ds_read_b128 v[170:173], v207 offset:51200
	ds_read_b128 v[174:177], v207 offset:52224
	ds_read_b128 v[208:211], v207 offset:53248
	ds_read_b128 v[212:215], v207 offset:54272
	ds_read_b128 v[232:235], v207 offset:55296
	ds_read_b128 v[242:245], v207 offset:56320
	global_load_lds_dwordx4 v[202:203], off
	v_lshl_add_u64 v[202:203], v[228:229], 0, s[20:21]
	s_add_i32 m0, s0, 0x2000
	s_add_i32 s0, s97, s4
	global_load_lds_dwordx4 v[202:203], off
	v_lshl_add_u64 v[202:203], v[230:231], 0, s[20:21]
	s_mov_b32 m0, s0
	s_nop 0
	global_load_lds_dwordx4 v[202:203], off
	v_lshl_add_u64 v[202:203], v[246:247], 0, s[20:21]
	s_add_i32 m0, s0, 0x2000
	s_nop 0
	global_load_lds_dwordx4 v[202:203], off
	v_lshl_add_u64 v[202:203], v[248:249], 0, s[20:21]
	s_mov_b32 m0, s53
	s_nop 0
	global_load_lds_dwordx4 v[202:203], off
	v_lshl_add_u64 v[202:203], v[236:237], 0, s[20:21]
	s_mov_b32 m0, s93
	s_nop 0
	global_load_lds_dwordx4 v[202:203], off
	s_waitcnt vmcnt(8)
	s_waitcnt lgkmcnt(0)
	s_barrier
	v_mfma_f32_16x16x32_bf16 v[60:63], v[130:133], v[162:165], v[60:63]
	v_mfma_f32_16x16x32_bf16 v[56:59], v[138:141], v[162:165], v[56:59]
	v_mfma_f32_16x16x32_bf16 v[48:51], v[130:133], v[170:173], v[48:51]
	v_mfma_f32_16x16x32_bf16 v[40:43], v[138:141], v[170:173], v[40:43]
	v_mfma_f32_16x16x32_bf16 v[32:35], v[130:133], v[208:211], v[32:35]
	v_mfma_f32_16x16x32_bf16 v[24:27], v[138:141], v[208:211], v[24:27]
	v_mfma_f32_16x16x32_bf16 v[16:19], v[130:133], v[232:235], v[16:19]
	v_mfma_f32_16x16x32_bf16 v[8:11], v[138:141], v[232:235], v[8:11]
	v_mfma_f32_16x16x32_bf16 v[60:63], v[134:137], v[166:169], v[60:63]
	v_mfma_f32_16x16x32_bf16 v[56:59], v[142:145], v[166:169], v[56:59]
	v_mfma_f32_16x16x32_bf16 v[48:51], v[134:137], v[174:177], v[48:51]
	v_mfma_f32_16x16x32_bf16 v[40:43], v[142:145], v[174:177], v[40:43]
	v_mfma_f32_16x16x32_bf16 v[32:35], v[134:137], v[212:215], v[32:35]
	v_mfma_f32_16x16x32_bf16 v[24:27], v[142:145], v[212:215], v[24:27]
	v_mfma_f32_16x16x32_bf16 v[16:19], v[134:137], v[242:245], v[16:19]
	v_mfma_f32_16x16x32_bf16 v[8:11], v[142:145], v[242:245], v[8:11]
	v_mfma_f32_16x16x32_bf16 v[52:55], v[146:149], v[162:165], v[52:55]
	v_mfma_f32_16x16x32_bf16 v[44:47], v[154:157], v[162:165], v[44:47]
	v_mfma_f32_16x16x32_bf16 v[36:39], v[146:149], v[170:173], v[36:39]
	v_mfma_f32_16x16x32_bf16 v[28:31], v[154:157], v[170:173], v[28:31]
	v_mfma_f32_16x16x32_bf16 v[20:23], v[146:149], v[208:211], v[20:23]
	v_mfma_f32_16x16x32_bf16 v[12:15], v[154:157], v[208:211], v[12:15]
	v_mfma_f32_16x16x32_bf16 v[4:7], v[146:149], v[232:235], v[4:7]
	v_mfma_f32_16x16x32_bf16 v[0:3], v[154:157], v[232:235], v[0:3]
	v_mfma_f32_16x16x32_bf16 v[52:55], v[150:153], v[166:169], v[52:55]
	v_mfma_f32_16x16x32_bf16 v[44:47], v[158:161], v[166:169], v[44:47]
	v_mfma_f32_16x16x32_bf16 v[36:39], v[150:153], v[174:177], v[36:39]
	v_mfma_f32_16x16x32_bf16 v[28:31], v[158:161], v[174:177], v[28:31]
	v_mfma_f32_16x16x32_bf16 v[20:23], v[150:153], v[212:215], v[20:23]
	v_mfma_f32_16x16x32_bf16 v[12:15], v[158:161], v[212:215], v[12:15]
	v_mfma_f32_16x16x32_bf16 v[4:7], v[150:153], v[242:245], v[4:7]
	v_mfma_f32_16x16x32_bf16 v[0:3], v[158:161], v[242:245], v[0:3]
	s_barrier
	s_add_u32 s45, s45, 0x100
	s_addc_u32 s94, s94, 0
	s_add_u32 s40, s40, 0x100
	s_addc_u32 s41, s41, 0
	s_cmp_ge_u32 s95, s58
	s_mov_b32 s0, s95
	s_cbranch_scc0 .LBB0_510
	s_and_b64 vcc, exec, s[82:83]
	s_cbranch_vccz .LBB0_513
	s_barrier

; #define PG8_WAIT_V(n) asm volatile("s_waitcnt vmcnt(" #n ")" ::: "memory")
; #define PG8_BAR __builtin_amdgcn_s_barrier()
; template <class Epi, class Sched, bool ALIGN_EPI = false, bool SP2 = false>
; __device__ __forceinline__ void gemm_phase(PG8_LAS unsigned char* lds, const Gemm g, const Sched& S, const Epi& E) {
;     ...
;     PG8_WAIT_V(0);
;     if constexpr (!ALIGN_EPI) { if (wr == 0) PG8_BAR; }
;     PG8_BAR;
.LBB0_519:
	s_setprio 0
	s_waitcnt vmcnt(0)
	s_barrier
	v_readlane_b32 s63, v254, 44
	v_readlane_b32 s33, v254, 45
	v_readlane_b32 s40, v254, 46
	v_readlane_b32 s41, v254, 47
	s_cbranch_execz .LBB0_425
	s_branch .LBB0_470
